# adds: init->P0 barrier removed (every WG writes the pointer table), hand-written residual epilogues with 16 loads in flight (5 of 6 sites)
# speedup vs baseline: 1.0719x; 1.0058x over previous
.LBB0_21:
	s_or_b64 exec, exec, s[4:5]
	s_load_dwordx2 s[68:69], s[0:1], 0x100
	s_mov_b64 s[20:21], s[66:67]
	v_mov_b32_e32 v0, v194
	s_mov_b32 s3, s64
	s_waitcnt lgkmcnt(0)
	s_mov_b64 s[4:5], s[68:69]
	s_nop 0
	v_cmp_eq_u32_e32 vcc, 0, v0
	s_and_saveexec_b64 s[22:23], vcc
	s_cbranch_execz .LBB0_23
	s_load_dwordx16 s[4:19], s[0:1], 0x0
	s_load_dwordx16 s[48:63], s[0:1], 0x40
	v_mov_b32_e32 v4, 0
	s_waitcnt lgkmcnt(0)
	v_mov_b32_e32 v0, s4
	v_mov_b32_e32 v1, s5
	v_mov_b32_e32 v2, s6
	v_mov_b32_e32 v3, s7
	global_store_dwordx4 v4, v[0:3], s[20:21]
	s_nop 1
	v_mov_b32_e32 v0, s8
	v_mov_b32_e32 v1, s9
	v_mov_b32_e32 v2, s10
	v_mov_b32_e32 v3, s11
	global_store_dwordx4 v4, v[0:3], s[20:21] offset:16
	s_nop 1
	v_mov_b32_e32 v0, s12
	v_mov_b32_e32 v1, s13
	v_mov_b32_e32 v2, s14
	v_mov_b32_e32 v3, s15
	global_store_dwordx4 v4, v[0:3], s[20:21] offset:32
	s_nop 1
	v_mov_b32_e32 v0, s16
	v_mov_b32_e32 v1, s17
	v_mov_b32_e32 v2, s18
	v_mov_b32_e32 v3, s19
	s_load_dwordx16 s[4:19], s[0:1], 0x80
	global_store_dwordx4 v4, v[0:3], s[20:21] offset:48
	s_nop 1
	v_mov_b32_e32 v0, s48
	v_mov_b32_e32 v1, s49
	v_mov_b32_e32 v2, s50
	v_mov_b32_e32 v3, s51
	global_store_dwordx4 v4, v[0:3], s[20:21] offset:64
	s_nop 1
	v_mov_b32_e32 v0, s52
	v_mov_b32_e32 v1, s53
	v_mov_b32_e32 v2, s54
	v_mov_b32_e32 v3, s55
	global_store_dwordx4 v4, v[0:3], s[20:21] offset:80
	s_nop 1
	v_mov_b32_e32 v0, s56
	v_mov_b32_e32 v1, s57
	v_mov_b32_e32 v2, s58
	v_mov_b32_e32 v3, s59
	global_store_dwordx4 v4, v[0:3], s[20:21] offset:96
	s_nop 1
	v_mov_b32_e32 v0, s60
	v_mov_b32_e32 v1, s61
	v_mov_b32_e32 v2, s62
	v_mov_b32_e32 v3, s63
	s_load_dwordx16 s[48:63], s[0:1], 0xc0
	global_store_dwordx4 v4, v[0:3], s[20:21] offset:112
	s_waitcnt lgkmcnt(0)
	s_nop 0
	v_mov_b32_e32 v0, s4
	v_mov_b32_e32 v1, s5
	v_mov_b32_e32 v2, s6
	v_mov_b32_e32 v3, s7
	global_store_dwordx4 v4, v[0:3], s[20:21] offset:128
	s_nop 1
	v_mov_b32_e32 v0, s8
	v_mov_b32_e32 v1, s9
	v_mov_b32_e32 v2, s10
	v_mov_b32_e32 v3, s11
	global_store_dwordx4 v4, v[0:3], s[20:21] offset:144
	s_nop 1
	v_mov_b32_e32 v0, s12
	v_mov_b32_e32 v1, s13
	v_mov_b32_e32 v2, s14
	v_mov_b32_e32 v3, s15
	global_store_dwordx4 v4, v[0:3], s[20:21] offset:160
	s_nop 1
	v_mov_b32_e32 v0, s16
	v_mov_b32_e32 v1, s17
	v_mov_b32_e32 v2, s18
	v_mov_b32_e32 v3, s19
	global_store_dwordx4 v4, v[0:3], s[20:21] offset:176
	s_nop 1
	v_mov_b32_e32 v0, s48
	v_mov_b32_e32 v1, s49
	v_mov_b32_e32 v2, s50
	v_mov_b32_e32 v3, s51
	global_store_dwordx4 v4, v[0:3], s[20:21] offset:192
	s_nop 1
	v_mov_b32_e32 v0, s52
	v_mov_b32_e32 v1, s53
	v_mov_b32_e32 v2, s54
	v_mov_b32_e32 v3, s55
	global_store_dwordx4 v4, v[0:3], s[20:21] offset:208
	s_nop 1
	v_mov_b32_e32 v0, s56
	v_mov_b32_e32 v1, s57
	v_mov_b32_e32 v2, s58
	v_mov_b32_e32 v3, s59
	global_store_dwordx4 v4, v[0:3], s[20:21] offset:224
	s_nop 1
	v_mov_b32_e32 v0, s60
	v_mov_b32_e32 v1, s61
	v_mov_b32_e32 v2, s62
	v_mov_b32_e32 v3, s63
	global_store_dwordx4 v4, v[0:3], s[20:21] offset:240

.LBB0_35:
	s_or_b64 exec, exec, s[10:11]
	s_add_u32 s75, s66, 0x1000
	s_addc_u32 s76, s67, 0
	s_waitcnt vmcnt(0)
	s_mov_b64 s[12:13], s[66:67]
	s_waitcnt lgkmcnt(0)
	s_barrier
	v_mov_b32_e32 v43, 0
	s_mov_b64 s[0:1], s[68:69]
	v_mov_b32_e32 v52, v194
	s_mov_b32 s20, s64
	global_load_dwordx2 v[40:41], v43, s[12:13] offset:216
	global_load_dwordx2 v[38:39], v43, s[12:13] offset:40
	v_ashrrev_i32_e32 v37, 6, v52
	s_lshl_b32 s11, s20, 3
	v_readfirstlane_b32 s0, v37
	s_add_i32 s10, s0, s33
	s_lshl_b32 s0, s0, 14
	s_add_i32 s14, s0, 0
	v_and_b32_e32 v36, 63, v52
	s_cmpk_lt_i32 s10, 0xb00
	s_cselect_b64 s[6:7], -1, 0
	s_cmpk_gt_i32 s10, 0xaff
	v_and_b32_e32 v54, 7, v52
	v_lshrrev_b32_e32 v53, 3, v36
	s_cbranch_scc1 .LBB0_106
	global_load_dwordx2 v[44:45], v43, s[12:13] offset:24
	global_load_dwordx4 v[0:3], v43, s[12:13] offset:8
	v_lshlrev_b32_e32 v42, 4, v54
	v_lshrrev_b32_e32 v6, 3, v36
	v_lshl_add_u64 v[4:5], s[12:13], 0, v[42:43]
	s_mov_b64 s[0:1], 0x100000
	v_add_u32_e32 v7, s14, v42
	v_mul_u32_u24_e32 v8, 0x84, v6
	v_mul_u32_u24_e32 v9, 0x420, v54
	v_lshl_add_u64 v[46:47], v[4:5], 0, s[0:1]
	v_lshlrev_b32_e32 v4, 2, v6
	v_lshlrev_b32_e32 v55, 2, v54
	v_add3_u32 v56, s14, v9, v4
	v_mov_b32_e32 v42, v6
	s_lshl_b32 s15, s10, 5
	s_lshl_b32 s16, s11, 5
	s_lshl_b32 s17, s10, 4
	s_lshl_b32 s18, s11, 4
	s_movk_i32 s19, 0x2c00
	v_add_u32_e32 v57, v7, v8
	s_movk_i32 s21, 0x7fff
	s_mov_b32 s22, 0xffff0000
	s_mov_b32 s23, s10
	s_branch .LBB0_90

.LBB0_769:
	s_mov_b64 s[0:1], s[66:67]
	s_mov_b64 s[6:7], s[68:69]
	v_mov_b32_e32 v6, v194
	v_and_b32_e32 v4, 63, v194
	v_lshrrev_b32_e32 v5, 6, v194
	v_and_b32_e32 v7, 1, v5
	v_lshl_or_b32 v4, v7, 8, v4
	v_lshrrev_b32_e32 v7, 1, v5
	s_and_b32 s12, s2, 1
	s_lshl_b32 s12, s12, 1
	v_add_u32_e32 v7, s12, v7
	v_lshl_or_b32 v4, v7, 6, v4
	s_lshr_b32 s12, s2, 1
	s_lshl_b32 s12, s12, 9
	v_or_b32_e32 v4, s12, v4
	v_mov_b32_e32 v7, 0x4000
	v_cmp_gt_u32_e32 vcc, 0x100, v194
	s_cmp_lt_u32 s2, 64
	s_cselect_b64 s[12:13], -1, 0
	s_nop 1
	s_and_b64 vcc, vcc, s[12:13]
	s_nop 1
	v_cndmask_b32_e32 v4, v7, v4, vcc
	v_mov_b32_e32 v5, 0
	s_mov_b64 s[10:11], 0x4000
	s_mov_b32 s6, s64
	v_cmp_gt_i64_e32 vcc, s[10:11], v[4:5]
	s_and_saveexec_b64 s[12:13], vcc
	s_cbranch_execz .LBB0_858
	v_mov_b32_e32 v7, 0
	global_load_dwordx2 v[8:9], v7, s[0:1] offset:72
	global_load_dwordx4 v[0:3], v7, s[0:1] offset:56
	v_and_b32_e32 v10, 63, v6
	v_lshlrev_b32_e32 v6, 1, v6
	v_and_b32_e32 v11, 0x7e, v6
	v_lshlrev_b32_e32 v6, 2, v11
	s_ashr_i32 s7, s6, 31
	v_lshl_add_u64 v[12:13], s[0:1], 0, v[6:7]
	v_lshlrev_b32_e32 v6, 1, v11
	s_lshl_b64 s[16:17], s[6:7], 9
	s_mov_b64 s[6:7], 0xf000000
	v_lshl_add_u64 v[14:15], s[0:1], 0, v[6:7]
	s_mov_b64 s[0:1], 0xb800000
	v_lshl_add_u64 v[12:13], v[12:13], 0, s[6:7]
	v_lshl_add_u64 v[14:15], v[14:15], 0, s[0:1]
	s_mov_b64 s[18:19], 0
	s_mov_b32 s26, 0x3fb8aa3b
	s_mov_b32 s27, 0xc2ce8ed0
	s_mov_b32 s28, 0x42b17218
	v_mov_b32_e32 v11, 0x7f800000
	s_brev_b32 s29, 18
	s_mov_b32 s30, 0xfe5163ab
	s_mov_b32 s31, 0x3c439041
	s_mov_b32 s34, 0xdb629599
	s_mov_b32 s35, 0xf534ddc0
	s_mov_b32 s36, 0xfc2757d1
	s_mov_b32 s37, 0x4e441529
	s_mov_b32 s38, 0xa2f9836e
	s_mov_b32 s39, 0x3fc90fda
	s_mov_b32 s40, 0x3f22f983
	s_mov_b32 s41, 0xbfc90fda
	v_mov_b32_e32 v26, 0x3c0881c4
	v_mov_b32_e32 v27, 0xbab64f3b
	s_brev_b32 s42, 1
	s_movk_i32 s43, 0x1f8
	s_movk_i32 s44, 0x180
	s_movk_i32 s45, 0x7fff
	s_mov_b32 s50, 0xffff0000
	s_movk_i32 s51, 0x600
	s_mov_b64 s[20:21], 0x3fff
	v_not_b32_e32 v28, 63
	v_not_b32_e32 v29, 31
	v_mov_b32_e32 v30, 0x7fc00000

.LBB0_858:
	s_or_b64 exec, exec, s[12:13]
	s_mov_b64 s[6:7], s[66:67]
	s_mov_b64 s[0:1], s[68:69]
	v_mov_b32_e32 v0, v194
	s_mov_b32 s38, s64
	s_abs_i32 s0, s38
	v_cvt_f32_u32_e32 v0, s0
	s_sub_i32 s11, 0, s0
	s_sub_i32 s77, s2, 64
	s_add_i32 s1, s77, s38
	v_rcp_iflag_f32_e32 v0, v0
	s_ashr_i32 s10, s1, 31
	s_abs_i32 s1, s1
	v_mov_b32_e32 v8, v194
	v_mul_f32_e32 v0, 0x4f7ffffe, v0
	v_cvt_u32_f32_e32 v0, v0
	s_nop 0
	v_readfirstlane_b32 s21, v8
	v_readfirstlane_b32 s12, v0
	s_mul_i32 s11, s11, s12
	s_mul_hi_u32 s11, s12, s11
	s_add_i32 s12, s12, s11
	s_mul_hi_u32 s11, s1, s12
	s_mul_i32 s11, s11, s0
	s_sub_i32 s1, s1, s11
	s_sub_i32 s11, s1, s0
	s_cmp_ge_u32 s1, s0
	s_cselect_b32 s1, s11, s1
	s_sub_i32 s11, s1, s0
	s_cmp_ge_u32 s1, s0
	s_cselect_b32 s0, s11, s1
	s_xor_b32 s0, s0, s10
	s_sub_i32 s39, s0, s10
	s_cmpk_gt_i32 s39, 0x7f
	s_cbranch_scc1 .LBB0_793
	s_ashr_i32 s40, s39, 31
	s_lshr_b32 s0, s40, 29
	s_add_i32 s12, s39, s0
	s_and_b32 s0, s12, -8
	s_sub_i32 s11, s39, s0
	s_cmp_gt_i32 s11, -1
	s_cbranch_scc0 .LBB0_772
	s_lshl_b32 s10, s11, 4
	s_ashr_i32 s0, s12, 3
	s_cbranch_execz .LBB0_773
	s_branch .LBB0_774

.LBB0_793:
	s_getreg_b32 s6, hwreg(HW_REG_XCC_ID, 0, 4)
	s_waitcnt vmcnt(0)
	s_barrier
	s_and_saveexec_b64 s[0:1], s[46:47]
	s_cbranch_execz .LBB0_910
	s_add_i32 s7, 0, 0x20160
	v_mov_b32_e32 v0, s7
	s_waitcnt vmcnt(0) expcnt(0) lgkmcnt(0)
	ds_read_b32 v2, v0
	s_add_i32 s7, 0, 0x20164
	v_mov_b32_e32 v0, s7
	ds_read_b32 v0, v0
	s_and_b32 s62, s6, 15
	s_waitcnt lgkmcnt(1)
	v_cmp_ne_u32_e32 vcc, 0, v2
	s_cbranch_vccnz .LBB0_874
	s_add_u32 s6, s66, 0x1200
	s_addc_u32 s7, s67, 0
	s_add_u32 s10, s66, 0x1400
	s_addc_u32 s11, s67, 0
	s_add_u32 s12, s66, 0x1500
	s_addc_u32 s13, s67, 0
	s_add_u32 s16, s66, 0x1600
	s_addc_u32 s17, s67, 0
	s_add_u32 s18, s66, 0x1700
	s_addc_u32 s19, s67, 0
	s_add_u32 s20, s66, 0x1800
	s_addc_u32 s21, s67, 0
	s_add_u32 s22, s66, 0x1900
	s_addc_u32 s23, s67, 0
	s_add_u32 s24, s66, 0x1a00
	s_addc_u32 s25, s67, 0
	s_add_u32 s26, s66, 0x1b00
	s_addc_u32 s27, s67, 0
	s_add_u32 s28, s66, 0x1c00
	s_addc_u32 s29, s67, 0
	s_add_u32 s30, s66, 0x1d00
	s_addc_u32 s31, s67, 0
	s_add_u32 s34, s66, 0x1e00
	s_addc_u32 s35, s67, 0
	s_add_u32 s36, s66, 0x1f00
	s_addc_u32 s37, s67, 0
	s_add_u32 s38, s66, 0x2000
	s_addc_u32 s39, s67, 0
	s_add_u32 s40, s66, 0x2100
	s_addc_u32 s41, s67, 0
	s_add_u32 s42, s66, 0x2200
	s_addc_u32 s43, s67, 0
	s_mul_i32 s63, s65, s74
	s_add_u32 s44, s66, 0x2300
	s_mul_i32 s63, s63, s64
	s_addc_u32 s45, s67, 0
	s_mov_b32 s70, 1
	v_mov_b32_e32 v16, 0
	s_branch .LBB0_862

.LBB0_1628:
	v_and_b32_e32 v252, 63, v194
	v_lshrrev_b32_e32 v253, 6, v194
	v_and_b32_e32 v254, 15, v252
	v_lshrrev_b32_e32 v255, 4, v252
	v_lshrrev_b32_e32 v252, 2, v253
	v_and_b32_e32 v253, 3, v253
	v_lshl_add_u32 v252, v252, 6, v254
	s_lshl_b32 s98, s38, 8
	v_add_u32_e32 v252, s98, v252
	v_lshlrev_b32_e32 v255, 3, v255
	v_lshl_add_u32 v255, v253, 5, v255
	s_lshl_b32 s98, s16, 8
	v_add_u32_e32 v255, s98, v255
	v_lshlrev_b32_e32 v234, 12, v252
	v_lshl_add_u32 v234, v255, 2, v234
	v_lshlrev_b32_e32 v235, 11, v252
	v_lshl_add_u32 v235, v255, 1, v235
	v_add_u32_e32 v235, 0x3800000, v235
	v_lshlrev_b32_e32 v236, 6, v252
	v_lshl_add_u32 v236, v253, 2, v236
	s_lshl_b32 s98, s16, 4
	s_add_i32 s98, s98, 0x3700000
	v_add_u32_e32 v236, s98, v236
	v_mov_b32_e32 v242, v234
	global_load_dwordx4 v[144:147], v242, s[68:69]
	global_load_dwordx4 v[156:159], v242, s[68:69] offset:16
	v_mov_b32_e32 v242, v234
	global_load_dwordx4 v[160:163], v242, s[68:69] offset:512
	global_load_dwordx4 v[164:167], v242, s[68:69] offset:528
	v_add_u32_e32 v242, 0x10000, v234
	global_load_dwordx4 v[168:171], v242, s[68:69]
	global_load_dwordx4 v[172:175], v242, s[68:69] offset:16
	v_add_u32_e32 v242, 0x10000, v234
	global_load_dwordx4 v[176:179], v242, s[68:69] offset:512
	global_load_dwordx4 v[180:183], v242, s[68:69] offset:528
	v_add_u32_e32 v242, 0x20000, v234
	global_load_dwordx4 v[184:187], v242, s[68:69]
	global_load_dwordx4 v[188:191], v242, s[68:69] offset:16
	v_add_u32_e32 v242, 0x20000, v234
	global_load_dwordx4 v[196:199], v242, s[68:69] offset:512
	global_load_dwordx4 v[200:203], v242, s[68:69] offset:528
	v_add_u32_e32 v242, 0x30000, v234
	global_load_dwordx4 v[204:207], v242, s[68:69]
	global_load_dwordx4 v[208:211], v242, s[68:69] offset:16
	v_add_u32_e32 v242, 0x30000, v234
	global_load_dwordx4 v[212:215], v242, s[68:69] offset:512
	global_load_dwordx4 v[216:219], v242, s[68:69] offset:528
	v_mov_b32_e32 v239, v234
	v_mov_b32_e32 v240, v235
	v_mov_b32_e32 v241, v236
	s_waitcnt vmcnt(14)
	v_add_f32_e32 v124, v124, v144
	v_add_f32_e32 v125, v125, v145
	v_add_f32_e32 v126, v126, v146
	v_add_f32_e32 v127, v127, v147
	v_add_f32_e32 v120, v120, v156
	v_add_f32_e32 v121, v121, v157
	v_add_f32_e32 v122, v122, v158
	v_add_f32_e32 v123, v123, v159
	v_add_u32_e32 v242, 0x80000, v234
	global_load_dwordx4 v[144:147], v242, s[68:69]
	global_load_dwordx4 v[156:159], v242, s[68:69] offset:16
	global_store_dwordx4 v239, v[124:127], s[68:69]
	global_store_dwordx4 v239, v[120:123], s[68:69] offset:16
	v_cvt_pk_bf16_f32 v244, v124, v125
	v_cvt_pk_bf16_f32 v245, v126, v127
	v_cvt_pk_bf16_f32 v246, v120, v121
	v_cvt_pk_bf16_f32 v247, v122, v123
	global_store_dwordx4 v240, v[244:247], s[66:67]
	v_mul_f32_e32 v237, v124, v124
	v_fmac_f32_e32 v237, v125, v125
	v_fmac_f32_e32 v237, v126, v126
	v_fmac_f32_e32 v237, v127, v127
	v_fmac_f32_e32 v237, v120, v120
	v_fmac_f32_e32 v237, v121, v121
	v_fmac_f32_e32 v237, v122, v122
	v_fmac_f32_e32 v237, v123, v123
	s_waitcnt vmcnt(17)
	v_add_f32_e32 v116, v116, v160
	v_add_f32_e32 v117, v117, v161
	v_add_f32_e32 v118, v118, v162
	v_add_f32_e32 v119, v119, v163
	v_add_f32_e32 v112, v112, v164
	v_add_f32_e32 v113, v113, v165
	v_add_f32_e32 v114, v114, v166
	v_add_f32_e32 v115, v115, v167
	v_add_u32_e32 v242, 0x80000, v234
	global_load_dwordx4 v[160:163], v242, s[68:69] offset:512
	global_load_dwordx4 v[164:167], v242, s[68:69] offset:528
	global_store_dwordx4 v239, v[116:119], s[68:69] offset:512
	global_store_dwordx4 v239, v[112:115], s[68:69] offset:528
	v_cvt_pk_bf16_f32 v248, v116, v117
	v_cvt_pk_bf16_f32 v249, v118, v119
	v_cvt_pk_bf16_f32 v250, v112, v113
	v_cvt_pk_bf16_f32 v251, v114, v115
	global_store_dwordx4 v240, v[248:251], s[66:67] offset:256
	v_fmac_f32_e32 v237, v116, v116
	v_fmac_f32_e32 v237, v117, v117
	v_fmac_f32_e32 v237, v118, v118
	v_fmac_f32_e32 v237, v119, v119
	v_fmac_f32_e32 v237, v112, v112
	v_fmac_f32_e32 v237, v113, v113
	v_fmac_f32_e32 v237, v114, v114
	v_fmac_f32_e32 v237, v115, v115
	v_mov_b32_e32 v238, v237
	s_nop 1
	v_permlane16_swap_b32_e32 v237, v238
	v_add_f32_e32 v237, v237, v238
	v_mov_b32_e32 v238, v237
	s_nop 1
	v_permlane32_swap_b32_e32 v237, v238
	v_add_f32_e32 v237, v237, v238
	global_store_dword v241, v237, s[66:67]
	v_add_u32_e32 v239, 0x10000, v234
	v_add_u32_e32 v240, 0x8000, v235
	v_add_u32_e32 v241, 0x400, v236
	s_waitcnt vmcnt(21)
	v_add_f32_e32 v108, v108, v168
	v_add_f32_e32 v109, v109, v169
	v_add_f32_e32 v110, v110, v170
	v_add_f32_e32 v111, v111, v171
	v_add_f32_e32 v104, v104, v172
	v_add_f32_e32 v105, v105, v173
	v_add_f32_e32 v106, v106, v174
	v_add_f32_e32 v107, v107, v175
	v_add_u32_e32 v242, 0x90000, v234
	global_load_dwordx4 v[168:171], v242, s[68:69]
	global_load_dwordx4 v[172:175], v242, s[68:69] offset:16
	global_store_dwordx4 v239, v[108:111], s[68:69]
	global_store_dwordx4 v239, v[104:107], s[68:69] offset:16
	v_cvt_pk_bf16_f32 v244, v108, v109
	v_cvt_pk_bf16_f32 v245, v110, v111
	v_cvt_pk_bf16_f32 v246, v104, v105
	v_cvt_pk_bf16_f32 v247, v106, v107
	global_store_dwordx4 v240, v[244:247], s[66:67]
	v_mul_f32_e32 v237, v108, v108
	v_fmac_f32_e32 v237, v109, v109
	v_fmac_f32_e32 v237, v110, v110
	v_fmac_f32_e32 v237, v111, v111
	v_fmac_f32_e32 v237, v104, v104
	v_fmac_f32_e32 v237, v105, v105
	v_fmac_f32_e32 v237, v106, v106
	v_fmac_f32_e32 v237, v107, v107
	s_waitcnt vmcnt(24)
	v_add_f32_e32 v100, v100, v176
	v_add_f32_e32 v101, v101, v177
	v_add_f32_e32 v102, v102, v178
	v_add_f32_e32 v103, v103, v179
	v_add_f32_e32 v96, v96, v180
	v_add_f32_e32 v97, v97, v181
	v_add_f32_e32 v98, v98, v182
	v_add_f32_e32 v99, v99, v183
	v_add_u32_e32 v242, 0x90000, v234
	global_load_dwordx4 v[176:179], v242, s[68:69] offset:512
	global_load_dwordx4 v[180:183], v242, s[68:69] offset:528
	global_store_dwordx4 v239, v[100:103], s[68:69] offset:512
	global_store_dwordx4 v239, v[96:99], s[68:69] offset:528
	v_cvt_pk_bf16_f32 v248, v100, v101
	v_cvt_pk_bf16_f32 v249, v102, v103
	v_cvt_pk_bf16_f32 v250, v96, v97
	v_cvt_pk_bf16_f32 v251, v98, v99
	global_store_dwordx4 v240, v[248:251], s[66:67] offset:256
	v_fmac_f32_e32 v237, v100, v100
	v_fmac_f32_e32 v237, v101, v101
	v_fmac_f32_e32 v237, v102, v102
	v_fmac_f32_e32 v237, v103, v103
	v_fmac_f32_e32 v237, v96, v96
	v_fmac_f32_e32 v237, v97, v97
	v_fmac_f32_e32 v237, v98, v98
	v_fmac_f32_e32 v237, v99, v99
	v_mov_b32_e32 v238, v237
	s_nop 1
	v_permlane16_swap_b32_e32 v237, v238
	v_add_f32_e32 v237, v237, v238
	v_mov_b32_e32 v238, v237
	s_nop 1
	v_permlane32_swap_b32_e32 v237, v238
	v_add_f32_e32 v237, v237, v238
	global_store_dword v241, v237, s[66:67]
	v_add_u32_e32 v239, 0x20000, v234
	v_add_u32_e32 v240, 0x10000, v235
	v_add_u32_e32 v241, 0x800, v236
	s_waitcnt vmcnt(28)
	v_add_f32_e32 v92, v92, v184
	v_add_f32_e32 v93, v93, v185
	v_add_f32_e32 v94, v94, v186
	v_add_f32_e32 v95, v95, v187
	v_add_f32_e32 v88, v88, v188
	v_add_f32_e32 v89, v89, v189
	v_add_f32_e32 v90, v90, v190
	v_add_f32_e32 v91, v91, v191
	v_add_u32_e32 v242, 0xa0000, v234
	global_load_dwordx4 v[184:187], v242, s[68:69]
	global_load_dwordx4 v[188:191], v242, s[68:69] offset:16
	global_store_dwordx4 v239, v[92:95], s[68:69]
	global_store_dwordx4 v239, v[88:91], s[68:69] offset:16
	v_cvt_pk_bf16_f32 v244, v92, v93
	v_cvt_pk_bf16_f32 v245, v94, v95
	v_cvt_pk_bf16_f32 v246, v88, v89
	v_cvt_pk_bf16_f32 v247, v90, v91
	global_store_dwordx4 v240, v[244:247], s[66:67]
	v_mul_f32_e32 v237, v92, v92
	v_fmac_f32_e32 v237, v93, v93
	v_fmac_f32_e32 v237, v94, v94
	v_fmac_f32_e32 v237, v95, v95
	v_fmac_f32_e32 v237, v88, v88
	v_fmac_f32_e32 v237, v89, v89
	v_fmac_f32_e32 v237, v90, v90
	v_fmac_f32_e32 v237, v91, v91
	s_waitcnt vmcnt(31)
	v_add_f32_e32 v84, v84, v196
	v_add_f32_e32 v85, v85, v197
	v_add_f32_e32 v86, v86, v198
	v_add_f32_e32 v87, v87, v199
	v_add_f32_e32 v80, v80, v200
	v_add_f32_e32 v81, v81, v201
	v_add_f32_e32 v82, v82, v202
	v_add_f32_e32 v83, v83, v203
	v_add_u32_e32 v242, 0xa0000, v234
	global_load_dwordx4 v[196:199], v242, s[68:69] offset:512
	global_load_dwordx4 v[200:203], v242, s[68:69] offset:528
	global_store_dwordx4 v239, v[84:87], s[68:69] offset:512
	global_store_dwordx4 v239, v[80:83], s[68:69] offset:528
	v_cvt_pk_bf16_f32 v248, v84, v85
	v_cvt_pk_bf16_f32 v249, v86, v87
	v_cvt_pk_bf16_f32 v250, v80, v81
	v_cvt_pk_bf16_f32 v251, v82, v83
	global_store_dwordx4 v240, v[248:251], s[66:67] offset:256
	v_fmac_f32_e32 v237, v84, v84
	v_fmac_f32_e32 v237, v85, v85
	v_fmac_f32_e32 v237, v86, v86
	v_fmac_f32_e32 v237, v87, v87
	v_fmac_f32_e32 v237, v80, v80
	v_fmac_f32_e32 v237, v81, v81
	v_fmac_f32_e32 v237, v82, v82
	v_fmac_f32_e32 v237, v83, v83
	v_mov_b32_e32 v238, v237
	s_nop 1
	v_permlane16_swap_b32_e32 v237, v238
	v_add_f32_e32 v237, v237, v238
	v_mov_b32_e32 v238, v237
	s_nop 1
	v_permlane32_swap_b32_e32 v237, v238
	v_add_f32_e32 v237, v237, v238
	global_store_dword v241, v237, s[66:67]
	v_add_u32_e32 v239, 0x30000, v234
	v_add_u32_e32 v240, 0x18000, v235
	v_add_u32_e32 v241, 0xc00, v236
	s_waitcnt vmcnt(35)
	v_add_f32_e32 v76, v76, v204
	v_add_f32_e32 v77, v77, v205
	v_add_f32_e32 v78, v78, v206
	v_add_f32_e32 v79, v79, v207
	v_add_f32_e32 v72, v72, v208
	v_add_f32_e32 v73, v73, v209
	v_add_f32_e32 v74, v74, v210
	v_add_f32_e32 v75, v75, v211
	v_add_u32_e32 v242, 0xb0000, v234
	global_load_dwordx4 v[204:207], v242, s[68:69]
	global_load_dwordx4 v[208:211], v242, s[68:69] offset:16
	global_store_dwordx4 v239, v[76:79], s[68:69]
	global_store_dwordx4 v239, v[72:75], s[68:69] offset:16
	v_cvt_pk_bf16_f32 v244, v76, v77
	v_cvt_pk_bf16_f32 v245, v78, v79
	v_cvt_pk_bf16_f32 v246, v72, v73
	v_cvt_pk_bf16_f32 v247, v74, v75
	global_store_dwordx4 v240, v[244:247], s[66:67]
	v_mul_f32_e32 v237, v76, v76
	v_fmac_f32_e32 v237, v77, v77
	v_fmac_f32_e32 v237, v78, v78
	v_fmac_f32_e32 v237, v79, v79
	v_fmac_f32_e32 v237, v72, v72
	v_fmac_f32_e32 v237, v73, v73
	v_fmac_f32_e32 v237, v74, v74
	v_fmac_f32_e32 v237, v75, v75
	s_waitcnt vmcnt(38)
	v_add_f32_e32 v68, v68, v212
	v_add_f32_e32 v69, v69, v213
	v_add_f32_e32 v70, v70, v214
	v_add_f32_e32 v71, v71, v215
	v_add_f32_e32 v64, v64, v216
	v_add_f32_e32 v65, v65, v217
	v_add_f32_e32 v66, v66, v218
	v_add_f32_e32 v67, v67, v219
	v_add_u32_e32 v242, 0xb0000, v234
	global_load_dwordx4 v[212:215], v242, s[68:69] offset:512
	global_load_dwordx4 v[216:219], v242, s[68:69] offset:528
	global_store_dwordx4 v239, v[68:71], s[68:69] offset:512
	global_store_dwordx4 v239, v[64:67], s[68:69] offset:528
	v_cvt_pk_bf16_f32 v248, v68, v69
	v_cvt_pk_bf16_f32 v249, v70, v71
	v_cvt_pk_bf16_f32 v250, v64, v65
	v_cvt_pk_bf16_f32 v251, v66, v67
	global_store_dwordx4 v240, v[248:251], s[66:67] offset:256
	v_fmac_f32_e32 v237, v68, v68
	v_fmac_f32_e32 v237, v69, v69
	v_fmac_f32_e32 v237, v70, v70
	v_fmac_f32_e32 v237, v71, v71
	v_fmac_f32_e32 v237, v64, v64
	v_fmac_f32_e32 v237, v65, v65
	v_fmac_f32_e32 v237, v66, v66
	v_fmac_f32_e32 v237, v67, v67
	v_mov_b32_e32 v238, v237
	s_nop 1
	v_permlane16_swap_b32_e32 v237, v238
	v_add_f32_e32 v237, v237, v238
	v_mov_b32_e32 v238, v237
	s_nop 1
	v_permlane32_swap_b32_e32 v237, v238
	v_add_f32_e32 v237, v237, v238
	global_store_dword v241, v237, s[66:67]
	v_add_u32_e32 v239, 0x80000, v234
	v_add_u32_e32 v240, 0x40000, v235
	v_add_u32_e32 v241, 0x2000, v236
	s_waitcnt vmcnt(42)
	v_add_f32_e32 v60, v60, v144
	v_add_f32_e32 v61, v61, v145
	v_add_f32_e32 v62, v62, v146
	v_add_f32_e32 v63, v63, v147
	v_add_f32_e32 v56, v56, v156
	v_add_f32_e32 v57, v57, v157
	v_add_f32_e32 v58, v58, v158
	v_add_f32_e32 v59, v59, v159
	global_store_dwordx4 v239, v[60:63], s[68:69]
	global_store_dwordx4 v239, v[56:59], s[68:69] offset:16
	v_cvt_pk_bf16_f32 v244, v60, v61
	v_cvt_pk_bf16_f32 v245, v62, v63
	v_cvt_pk_bf16_f32 v246, v56, v57
	v_cvt_pk_bf16_f32 v247, v58, v59
	global_store_dwordx4 v240, v[244:247], s[66:67]
	v_mul_f32_e32 v237, v60, v60
	v_fmac_f32_e32 v237, v61, v61
	v_fmac_f32_e32 v237, v62, v62
	v_fmac_f32_e32 v237, v63, v63
	v_fmac_f32_e32 v237, v56, v56
	v_fmac_f32_e32 v237, v57, v57
	v_fmac_f32_e32 v237, v58, v58
	v_fmac_f32_e32 v237, v59, v59
	s_waitcnt vmcnt(40)
	v_add_f32_e32 v52, v52, v160
	v_add_f32_e32 v53, v53, v161
	v_add_f32_e32 v54, v54, v162
	v_add_f32_e32 v55, v55, v163
	v_add_f32_e32 v48, v48, v164
	v_add_f32_e32 v49, v49, v165
	v_add_f32_e32 v50, v50, v166
	v_add_f32_e32 v51, v51, v167
	global_store_dwordx4 v239, v[52:55], s[68:69] offset:512
	global_store_dwordx4 v239, v[48:51], s[68:69] offset:528
	v_cvt_pk_bf16_f32 v248, v52, v53
	v_cvt_pk_bf16_f32 v249, v54, v55
	v_cvt_pk_bf16_f32 v250, v48, v49
	v_cvt_pk_bf16_f32 v251, v50, v51
	global_store_dwordx4 v240, v[248:251], s[66:67] offset:256
	v_fmac_f32_e32 v237, v52, v52
	v_fmac_f32_e32 v237, v53, v53
	v_fmac_f32_e32 v237, v54, v54
	v_fmac_f32_e32 v237, v55, v55
	v_fmac_f32_e32 v237, v48, v48
	v_fmac_f32_e32 v237, v49, v49
	v_fmac_f32_e32 v237, v50, v50
	v_fmac_f32_e32 v237, v51, v51
	v_mov_b32_e32 v238, v237
	s_nop 1
	v_permlane16_swap_b32_e32 v237, v238
	v_add_f32_e32 v237, v237, v238
	v_mov_b32_e32 v238, v237
	s_nop 1
	v_permlane32_swap_b32_e32 v237, v238
	v_add_f32_e32 v237, v237, v238
	global_store_dword v241, v237, s[66:67]
	v_add_u32_e32 v239, 0x90000, v234
	v_add_u32_e32 v240, 0x48000, v235
	v_add_u32_e32 v241, 0x2400, v236
	s_waitcnt vmcnt(38)
	v_add_f32_e32 v44, v44, v168
	v_add_f32_e32 v45, v45, v169
	v_add_f32_e32 v46, v46, v170
	v_add_f32_e32 v47, v47, v171
	v_add_f32_e32 v40, v40, v172
	v_add_f32_e32 v41, v41, v173
	v_add_f32_e32 v42, v42, v174
	v_add_f32_e32 v43, v43, v175
	global_store_dwordx4 v239, v[44:47], s[68:69]
	global_store_dwordx4 v239, v[40:43], s[68:69] offset:16
	v_cvt_pk_bf16_f32 v244, v44, v45
	v_cvt_pk_bf16_f32 v245, v46, v47
	v_cvt_pk_bf16_f32 v246, v40, v41
	v_cvt_pk_bf16_f32 v247, v42, v43
	global_store_dwordx4 v240, v[244:247], s[66:67]
	v_mul_f32_e32 v237, v44, v44
	v_fmac_f32_e32 v237, v45, v45
	v_fmac_f32_e32 v237, v46, v46
	v_fmac_f32_e32 v237, v47, v47
	v_fmac_f32_e32 v237, v40, v40
	v_fmac_f32_e32 v237, v41, v41
	v_fmac_f32_e32 v237, v42, v42
	v_fmac_f32_e32 v237, v43, v43
	s_waitcnt vmcnt(36)
	v_add_f32_e32 v36, v36, v176
	v_add_f32_e32 v37, v37, v177
	v_add_f32_e32 v38, v38, v178
	v_add_f32_e32 v39, v39, v179
	v_add_f32_e32 v32, v32, v180
	v_add_f32_e32 v33, v33, v181
	v_add_f32_e32 v34, v34, v182
	v_add_f32_e32 v35, v35, v183
	global_store_dwordx4 v239, v[36:39], s[68:69] offset:512
	global_store_dwordx4 v239, v[32:35], s[68:69] offset:528
	v_cvt_pk_bf16_f32 v248, v36, v37
	v_cvt_pk_bf16_f32 v249, v38, v39
	v_cvt_pk_bf16_f32 v250, v32, v33
	v_cvt_pk_bf16_f32 v251, v34, v35
	global_store_dwordx4 v240, v[248:251], s[66:67] offset:256
	v_fmac_f32_e32 v237, v36, v36
	v_fmac_f32_e32 v237, v37, v37
	v_fmac_f32_e32 v237, v38, v38
	v_fmac_f32_e32 v237, v39, v39
	v_fmac_f32_e32 v237, v32, v32
	v_fmac_f32_e32 v237, v33, v33
	v_fmac_f32_e32 v237, v34, v34
	v_fmac_f32_e32 v237, v35, v35
	v_mov_b32_e32 v238, v237
	s_nop 1
	v_permlane16_swap_b32_e32 v237, v238
	v_add_f32_e32 v237, v237, v238
	v_mov_b32_e32 v238, v237
	s_nop 1
	v_permlane32_swap_b32_e32 v237, v238
	v_add_f32_e32 v237, v237, v238
	global_store_dword v241, v237, s[66:67]
	v_add_u32_e32 v239, 0xa0000, v234
	v_add_u32_e32 v240, 0x50000, v235
	v_add_u32_e32 v241, 0x2800, v236
	s_waitcnt vmcnt(34)
	v_add_f32_e32 v28, v28, v184
	v_add_f32_e32 v29, v29, v185
	v_add_f32_e32 v30, v30, v186
	v_add_f32_e32 v31, v31, v187
	v_add_f32_e32 v24, v24, v188
	v_add_f32_e32 v25, v25, v189
	v_add_f32_e32 v26, v26, v190
	v_add_f32_e32 v27, v27, v191
	global_store_dwordx4 v239, v[28:31], s[68:69]
	global_store_dwordx4 v239, v[24:27], s[68:69] offset:16
	v_cvt_pk_bf16_f32 v244, v28, v29
	v_cvt_pk_bf16_f32 v245, v30, v31
	v_cvt_pk_bf16_f32 v246, v24, v25
	v_cvt_pk_bf16_f32 v247, v26, v27
	global_store_dwordx4 v240, v[244:247], s[66:67]
	v_mul_f32_e32 v237, v28, v28
	v_fmac_f32_e32 v237, v29, v29
	v_fmac_f32_e32 v237, v30, v30
	v_fmac_f32_e32 v237, v31, v31
	v_fmac_f32_e32 v237, v24, v24
	v_fmac_f32_e32 v237, v25, v25
	v_fmac_f32_e32 v237, v26, v26
	v_fmac_f32_e32 v237, v27, v27
	s_waitcnt vmcnt(32)
	v_add_f32_e32 v20, v20, v196
	v_add_f32_e32 v21, v21, v197
	v_add_f32_e32 v22, v22, v198
	v_add_f32_e32 v23, v23, v199
	v_add_f32_e32 v16, v16, v200
	v_add_f32_e32 v17, v17, v201
	v_add_f32_e32 v18, v18, v202
	v_add_f32_e32 v19, v19, v203
	global_store_dwordx4 v239, v[20:23], s[68:69] offset:512
	global_store_dwordx4 v239, v[16:19], s[68:69] offset:528
	v_cvt_pk_bf16_f32 v248, v20, v21
	v_cvt_pk_bf16_f32 v249, v22, v23
	v_cvt_pk_bf16_f32 v250, v16, v17
	v_cvt_pk_bf16_f32 v251, v18, v19
	global_store_dwordx4 v240, v[248:251], s[66:67] offset:256
	v_fmac_f32_e32 v237, v20, v20
	v_fmac_f32_e32 v237, v21, v21
	v_fmac_f32_e32 v237, v22, v22
	v_fmac_f32_e32 v237, v23, v23
	v_fmac_f32_e32 v237, v16, v16
	v_fmac_f32_e32 v237, v17, v17
	v_fmac_f32_e32 v237, v18, v18
	v_fmac_f32_e32 v237, v19, v19
	v_mov_b32_e32 v238, v237
	s_nop 1
	v_permlane16_swap_b32_e32 v237, v238
	v_add_f32_e32 v237, v237, v238
	v_mov_b32_e32 v238, v237
	s_nop 1
	v_permlane32_swap_b32_e32 v237, v238
	v_add_f32_e32 v237, v237, v238
	global_store_dword v241, v237, s[66:67]
	v_add_u32_e32 v239, 0xb0000, v234
	v_add_u32_e32 v240, 0x58000, v235
	v_add_u32_e32 v241, 0x2c00, v236
	s_waitcnt vmcnt(30)
	v_add_f32_e32 v12, v12, v204
	v_add_f32_e32 v13, v13, v205
	v_add_f32_e32 v14, v14, v206
	v_add_f32_e32 v15, v15, v207
	v_add_f32_e32 v8, v8, v208
	v_add_f32_e32 v9, v9, v209
	v_add_f32_e32 v10, v10, v210
	v_add_f32_e32 v11, v11, v211
	global_store_dwordx4 v239, v[12:15], s[68:69]
	global_store_dwordx4 v239, v[8:11], s[68:69] offset:16
	v_cvt_pk_bf16_f32 v244, v12, v13
	v_cvt_pk_bf16_f32 v245, v14, v15
	v_cvt_pk_bf16_f32 v246, v8, v9
	v_cvt_pk_bf16_f32 v247, v10, v11
	global_store_dwordx4 v240, v[244:247], s[66:67]
	v_mul_f32_e32 v237, v12, v12
	v_fmac_f32_e32 v237, v13, v13
	v_fmac_f32_e32 v237, v14, v14
	v_fmac_f32_e32 v237, v15, v15
	v_fmac_f32_e32 v237, v8, v8
	v_fmac_f32_e32 v237, v9, v9
	v_fmac_f32_e32 v237, v10, v10
	v_fmac_f32_e32 v237, v11, v11
	s_waitcnt vmcnt(28)
	v_add_f32_e32 v4, v4, v212
	v_add_f32_e32 v5, v5, v213
	v_add_f32_e32 v6, v6, v214
	v_add_f32_e32 v7, v7, v215
	v_add_f32_e32 v0, v0, v216
	v_add_f32_e32 v1, v1, v217
	v_add_f32_e32 v2, v2, v218
	v_add_f32_e32 v3, v3, v219
	global_store_dwordx4 v239, v[4:7], s[68:69] offset:512
	global_store_dwordx4 v239, v[0:3], s[68:69] offset:528
	v_cvt_pk_bf16_f32 v248, v4, v5
	v_cvt_pk_bf16_f32 v249, v6, v7
	v_cvt_pk_bf16_f32 v250, v0, v1
	v_cvt_pk_bf16_f32 v251, v2, v3
	global_store_dwordx4 v240, v[248:251], s[66:67] offset:256
	v_fmac_f32_e32 v237, v4, v4
	v_fmac_f32_e32 v237, v5, v5
	v_fmac_f32_e32 v237, v6, v6
	v_fmac_f32_e32 v237, v7, v7
	v_fmac_f32_e32 v237, v0, v0
	v_fmac_f32_e32 v237, v1, v1
	v_fmac_f32_e32 v237, v2, v2
	v_fmac_f32_e32 v237, v3, v3
	v_mov_b32_e32 v238, v237
	s_nop 1
	v_permlane16_swap_b32_e32 v237, v238
	v_add_f32_e32 v237, v237, v238
	v_mov_b32_e32 v238, v237
	s_nop 1
	v_permlane32_swap_b32_e32 v237, v238
	v_add_f32_e32 v237, v237, v238
	global_store_dword v241, v237, s[66:67]
	s_andn2_b64 vcc, exec, s[14:15]
	s_mov_b64 s[14:15], -1
	s_cbranch_vccnz .LBB0_1617
	s_andn2_b64 vcc, exec, s[18:19]
	s_cbranch_vccnz .LBB0_1616
	s_barrier
	s_branch .LBB0_1616

.LBB0_1794:
	v_and_b32_e32 v252, 63, v194
	v_lshrrev_b32_e32 v253, 6, v194
	v_and_b32_e32 v254, 15, v252
	v_lshrrev_b32_e32 v255, 4, v252
	v_lshrrev_b32_e32 v252, 2, v253
	v_and_b32_e32 v253, 3, v253
	v_lshl_add_u32 v252, v252, 6, v254
	s_lshl_b32 s98, s82, 8
	v_add_u32_e32 v252, s98, v252
	v_lshlrev_b32_e32 v255, 3, v255
	v_lshl_add_u32 v255, v253, 5, v255
	s_lshl_b32 s98, s20, 8
	v_add_u32_e32 v255, s98, v255
	v_lshlrev_b32_e32 v234, 12, v252
	v_lshl_add_u32 v234, v255, 2, v234
	v_lshlrev_b32_e32 v235, 11, v252
	v_lshl_add_u32 v235, v255, 1, v235
	v_add_u32_e32 v235, 0x3800000, v235
	v_lshlrev_b32_e32 v236, 6, v252
	v_lshl_add_u32 v236, v253, 2, v236
	s_lshl_b32 s98, s20, 4
	s_add_i32 s98, s98, 0x3500000
	v_add_u32_e32 v236, s98, v236
	v_mov_b32_e32 v242, v234
	global_load_dwordx4 v[144:147], v242, s[68:69]
	global_load_dwordx4 v[156:159], v242, s[68:69] offset:16
	v_mov_b32_e32 v242, v234
	global_load_dwordx4 v[160:163], v242, s[68:69] offset:512
	global_load_dwordx4 v[164:167], v242, s[68:69] offset:528
	v_add_u32_e32 v242, 0x10000, v234
	global_load_dwordx4 v[168:171], v242, s[68:69]
	global_load_dwordx4 v[172:175], v242, s[68:69] offset:16
	v_add_u32_e32 v242, 0x10000, v234
	global_load_dwordx4 v[176:179], v242, s[68:69] offset:512
	global_load_dwordx4 v[180:183], v242, s[68:69] offset:528
	v_add_u32_e32 v242, 0x20000, v234
	global_load_dwordx4 v[184:187], v242, s[68:69]
	global_load_dwordx4 v[188:191], v242, s[68:69] offset:16
	v_add_u32_e32 v242, 0x20000, v234
	global_load_dwordx4 v[196:199], v242, s[68:69] offset:512
	global_load_dwordx4 v[200:203], v242, s[68:69] offset:528
	v_add_u32_e32 v242, 0x30000, v234
	global_load_dwordx4 v[204:207], v242, s[68:69]
	global_load_dwordx4 v[208:211], v242, s[68:69] offset:16
	v_add_u32_e32 v242, 0x30000, v234
	global_load_dwordx4 v[212:215], v242, s[68:69] offset:512
	global_load_dwordx4 v[216:219], v242, s[68:69] offset:528
	v_mov_b32_e32 v239, v234
	v_mov_b32_e32 v240, v235
	v_mov_b32_e32 v241, v236
	s_waitcnt vmcnt(14)
	v_fma_f32 v124, v124, 0.5, v144
	v_fma_f32 v125, v125, 0.5, v145
	v_fma_f32 v126, v126, 0.5, v146
	v_fma_f32 v127, v127, 0.5, v147
	v_fma_f32 v120, v120, 0.5, v156
	v_fma_f32 v121, v121, 0.5, v157
	v_fma_f32 v122, v122, 0.5, v158
	v_fma_f32 v123, v123, 0.5, v159
	v_add_u32_e32 v242, 0x80000, v234
	global_load_dwordx4 v[144:147], v242, s[68:69]
	global_load_dwordx4 v[156:159], v242, s[68:69] offset:16
	global_store_dwordx4 v239, v[124:127], s[68:69]
	global_store_dwordx4 v239, v[120:123], s[68:69] offset:16
	v_cvt_pk_bf16_f32 v244, v124, v125
	v_cvt_pk_bf16_f32 v245, v126, v127
	v_cvt_pk_bf16_f32 v246, v120, v121
	v_cvt_pk_bf16_f32 v247, v122, v123
	global_store_dwordx4 v240, v[244:247], s[66:67]
	v_mul_f32_e32 v237, v124, v124
	v_fmac_f32_e32 v237, v125, v125
	v_fmac_f32_e32 v237, v126, v126
	v_fmac_f32_e32 v237, v127, v127
	v_fmac_f32_e32 v237, v120, v120
	v_fmac_f32_e32 v237, v121, v121
	v_fmac_f32_e32 v237, v122, v122
	v_fmac_f32_e32 v237, v123, v123
	s_waitcnt vmcnt(17)
	v_fma_f32 v116, v116, 0.5, v160
	v_fma_f32 v117, v117, 0.5, v161
	v_fma_f32 v118, v118, 0.5, v162
	v_fma_f32 v119, v119, 0.5, v163
	v_fma_f32 v112, v112, 0.5, v164
	v_fma_f32 v113, v113, 0.5, v165
	v_fma_f32 v114, v114, 0.5, v166
	v_fma_f32 v115, v115, 0.5, v167
	v_add_u32_e32 v242, 0x80000, v234
	global_load_dwordx4 v[160:163], v242, s[68:69] offset:512
	global_load_dwordx4 v[164:167], v242, s[68:69] offset:528
	global_store_dwordx4 v239, v[116:119], s[68:69] offset:512
	global_store_dwordx4 v239, v[112:115], s[68:69] offset:528
	v_cvt_pk_bf16_f32 v248, v116, v117
	v_cvt_pk_bf16_f32 v249, v118, v119
	v_cvt_pk_bf16_f32 v250, v112, v113
	v_cvt_pk_bf16_f32 v251, v114, v115
	global_store_dwordx4 v240, v[248:251], s[66:67] offset:256
	v_fmac_f32_e32 v237, v116, v116
	v_fmac_f32_e32 v237, v117, v117
	v_fmac_f32_e32 v237, v118, v118
	v_fmac_f32_e32 v237, v119, v119
	v_fmac_f32_e32 v237, v112, v112
	v_fmac_f32_e32 v237, v113, v113
	v_fmac_f32_e32 v237, v114, v114
	v_fmac_f32_e32 v237, v115, v115
	v_mov_b32_e32 v238, v237
	s_nop 1
	v_permlane16_swap_b32_e32 v237, v238
	v_add_f32_e32 v237, v237, v238
	v_mov_b32_e32 v238, v237
	s_nop 1
	v_permlane32_swap_b32_e32 v237, v238
	v_add_f32_e32 v237, v237, v238
	global_store_dword v241, v237, s[66:67]
	v_add_u32_e32 v239, 0x10000, v234
	v_add_u32_e32 v240, 0x8000, v235
	v_add_u32_e32 v241, 0x400, v236
	s_waitcnt vmcnt(21)
	v_fma_f32 v108, v108, 0.5, v168
	v_fma_f32 v109, v109, 0.5, v169
	v_fma_f32 v110, v110, 0.5, v170
	v_fma_f32 v111, v111, 0.5, v171
	v_fma_f32 v104, v104, 0.5, v172
	v_fma_f32 v105, v105, 0.5, v173
	v_fma_f32 v106, v106, 0.5, v174
	v_fma_f32 v107, v107, 0.5, v175
	v_add_u32_e32 v242, 0x90000, v234
	global_load_dwordx4 v[168:171], v242, s[68:69]
	global_load_dwordx4 v[172:175], v242, s[68:69] offset:16
	global_store_dwordx4 v239, v[108:111], s[68:69]
	global_store_dwordx4 v239, v[104:107], s[68:69] offset:16
	v_cvt_pk_bf16_f32 v244, v108, v109
	v_cvt_pk_bf16_f32 v245, v110, v111
	v_cvt_pk_bf16_f32 v246, v104, v105
	v_cvt_pk_bf16_f32 v247, v106, v107
	global_store_dwordx4 v240, v[244:247], s[66:67]
	v_mul_f32_e32 v237, v108, v108
	v_fmac_f32_e32 v237, v109, v109
	v_fmac_f32_e32 v237, v110, v110
	v_fmac_f32_e32 v237, v111, v111
	v_fmac_f32_e32 v237, v104, v104
	v_fmac_f32_e32 v237, v105, v105
	v_fmac_f32_e32 v237, v106, v106
	v_fmac_f32_e32 v237, v107, v107
	s_waitcnt vmcnt(24)
	v_fma_f32 v100, v100, 0.5, v176
	v_fma_f32 v101, v101, 0.5, v177
	v_fma_f32 v102, v102, 0.5, v178
	v_fma_f32 v103, v103, 0.5, v179
	v_fma_f32 v96, v96, 0.5, v180
	v_fma_f32 v97, v97, 0.5, v181
	v_fma_f32 v98, v98, 0.5, v182
	v_fma_f32 v99, v99, 0.5, v183
	v_add_u32_e32 v242, 0x90000, v234
	global_load_dwordx4 v[176:179], v242, s[68:69] offset:512
	global_load_dwordx4 v[180:183], v242, s[68:69] offset:528
	global_store_dwordx4 v239, v[100:103], s[68:69] offset:512
	global_store_dwordx4 v239, v[96:99], s[68:69] offset:528
	v_cvt_pk_bf16_f32 v248, v100, v101
	v_cvt_pk_bf16_f32 v249, v102, v103
	v_cvt_pk_bf16_f32 v250, v96, v97
	v_cvt_pk_bf16_f32 v251, v98, v99
	global_store_dwordx4 v240, v[248:251], s[66:67] offset:256
	v_fmac_f32_e32 v237, v100, v100
	v_fmac_f32_e32 v237, v101, v101
	v_fmac_f32_e32 v237, v102, v102
	v_fmac_f32_e32 v237, v103, v103
	v_fmac_f32_e32 v237, v96, v96
	v_fmac_f32_e32 v237, v97, v97
	v_fmac_f32_e32 v237, v98, v98
	v_fmac_f32_e32 v237, v99, v99
	v_mov_b32_e32 v238, v237
	s_nop 1
	v_permlane16_swap_b32_e32 v237, v238
	v_add_f32_e32 v237, v237, v238
	v_mov_b32_e32 v238, v237
	s_nop 1
	v_permlane32_swap_b32_e32 v237, v238
	v_add_f32_e32 v237, v237, v238
	global_store_dword v241, v237, s[66:67]
	v_add_u32_e32 v239, 0x20000, v234
	v_add_u32_e32 v240, 0x10000, v235
	v_add_u32_e32 v241, 0x800, v236
	s_waitcnt vmcnt(28)
	v_fma_f32 v92, v92, 0.5, v184
	v_fma_f32 v93, v93, 0.5, v185
	v_fma_f32 v94, v94, 0.5, v186
	v_fma_f32 v95, v95, 0.5, v187
	v_fma_f32 v88, v88, 0.5, v188
	v_fma_f32 v89, v89, 0.5, v189
	v_fma_f32 v90, v90, 0.5, v190
	v_fma_f32 v91, v91, 0.5, v191
	v_add_u32_e32 v242, 0xa0000, v234
	global_load_dwordx4 v[184:187], v242, s[68:69]
	global_load_dwordx4 v[188:191], v242, s[68:69] offset:16
	global_store_dwordx4 v239, v[92:95], s[68:69]
	global_store_dwordx4 v239, v[88:91], s[68:69] offset:16
	v_cvt_pk_bf16_f32 v244, v92, v93
	v_cvt_pk_bf16_f32 v245, v94, v95
	v_cvt_pk_bf16_f32 v246, v88, v89
	v_cvt_pk_bf16_f32 v247, v90, v91
	global_store_dwordx4 v240, v[244:247], s[66:67]
	v_mul_f32_e32 v237, v92, v92
	v_fmac_f32_e32 v237, v93, v93
	v_fmac_f32_e32 v237, v94, v94
	v_fmac_f32_e32 v237, v95, v95
	v_fmac_f32_e32 v237, v88, v88
	v_fmac_f32_e32 v237, v89, v89
	v_fmac_f32_e32 v237, v90, v90
	v_fmac_f32_e32 v237, v91, v91
	s_waitcnt vmcnt(31)
	v_fma_f32 v84, v84, 0.5, v196
	v_fma_f32 v85, v85, 0.5, v197
	v_fma_f32 v86, v86, 0.5, v198
	v_fma_f32 v87, v87, 0.5, v199
	v_fma_f32 v80, v80, 0.5, v200
	v_fma_f32 v81, v81, 0.5, v201
	v_fma_f32 v82, v82, 0.5, v202
	v_fma_f32 v83, v83, 0.5, v203
	v_add_u32_e32 v242, 0xa0000, v234
	global_load_dwordx4 v[196:199], v242, s[68:69] offset:512
	global_load_dwordx4 v[200:203], v242, s[68:69] offset:528
	global_store_dwordx4 v239, v[84:87], s[68:69] offset:512
	global_store_dwordx4 v239, v[80:83], s[68:69] offset:528
	v_cvt_pk_bf16_f32 v248, v84, v85
	v_cvt_pk_bf16_f32 v249, v86, v87
	v_cvt_pk_bf16_f32 v250, v80, v81
	v_cvt_pk_bf16_f32 v251, v82, v83
	global_store_dwordx4 v240, v[248:251], s[66:67] offset:256
	v_fmac_f32_e32 v237, v84, v84
	v_fmac_f32_e32 v237, v85, v85
	v_fmac_f32_e32 v237, v86, v86
	v_fmac_f32_e32 v237, v87, v87
	v_fmac_f32_e32 v237, v80, v80
	v_fmac_f32_e32 v237, v81, v81
	v_fmac_f32_e32 v237, v82, v82
	v_fmac_f32_e32 v237, v83, v83
	v_mov_b32_e32 v238, v237
	s_nop 1
	v_permlane16_swap_b32_e32 v237, v238
	v_add_f32_e32 v237, v237, v238
	v_mov_b32_e32 v238, v237
	s_nop 1
	v_permlane32_swap_b32_e32 v237, v238
	v_add_f32_e32 v237, v237, v238
	global_store_dword v241, v237, s[66:67]
	v_add_u32_e32 v239, 0x30000, v234
	v_add_u32_e32 v240, 0x18000, v235
	v_add_u32_e32 v241, 0xc00, v236
	s_waitcnt vmcnt(35)
	v_fma_f32 v76, v76, 0.5, v204
	v_fma_f32 v77, v77, 0.5, v205
	v_fma_f32 v78, v78, 0.5, v206
	v_fma_f32 v79, v79, 0.5, v207
	v_fma_f32 v72, v72, 0.5, v208
	v_fma_f32 v73, v73, 0.5, v209
	v_fma_f32 v74, v74, 0.5, v210
	v_fma_f32 v75, v75, 0.5, v211
	v_add_u32_e32 v242, 0xb0000, v234
	global_load_dwordx4 v[204:207], v242, s[68:69]
	global_load_dwordx4 v[208:211], v242, s[68:69] offset:16
	global_store_dwordx4 v239, v[76:79], s[68:69]
	global_store_dwordx4 v239, v[72:75], s[68:69] offset:16
	v_cvt_pk_bf16_f32 v244, v76, v77
	v_cvt_pk_bf16_f32 v245, v78, v79
	v_cvt_pk_bf16_f32 v246, v72, v73
	v_cvt_pk_bf16_f32 v247, v74, v75
	global_store_dwordx4 v240, v[244:247], s[66:67]
	v_mul_f32_e32 v237, v76, v76
	v_fmac_f32_e32 v237, v77, v77
	v_fmac_f32_e32 v237, v78, v78
	v_fmac_f32_e32 v237, v79, v79
	v_fmac_f32_e32 v237, v72, v72
	v_fmac_f32_e32 v237, v73, v73
	v_fmac_f32_e32 v237, v74, v74
	v_fmac_f32_e32 v237, v75, v75
	s_waitcnt vmcnt(38)
	v_fma_f32 v68, v68, 0.5, v212
	v_fma_f32 v69, v69, 0.5, v213
	v_fma_f32 v70, v70, 0.5, v214
	v_fma_f32 v71, v71, 0.5, v215
	v_fma_f32 v64, v64, 0.5, v216
	v_fma_f32 v65, v65, 0.5, v217
	v_fma_f32 v66, v66, 0.5, v218
	v_fma_f32 v67, v67, 0.5, v219
	v_add_u32_e32 v242, 0xb0000, v234
	global_load_dwordx4 v[212:215], v242, s[68:69] offset:512
	global_load_dwordx4 v[216:219], v242, s[68:69] offset:528
	global_store_dwordx4 v239, v[68:71], s[68:69] offset:512
	global_store_dwordx4 v239, v[64:67], s[68:69] offset:528
	v_cvt_pk_bf16_f32 v248, v68, v69
	v_cvt_pk_bf16_f32 v249, v70, v71
	v_cvt_pk_bf16_f32 v250, v64, v65
	v_cvt_pk_bf16_f32 v251, v66, v67
	global_store_dwordx4 v240, v[248:251], s[66:67] offset:256
	v_fmac_f32_e32 v237, v68, v68
	v_fmac_f32_e32 v237, v69, v69
	v_fmac_f32_e32 v237, v70, v70
	v_fmac_f32_e32 v237, v71, v71
	v_fmac_f32_e32 v237, v64, v64
	v_fmac_f32_e32 v237, v65, v65
	v_fmac_f32_e32 v237, v66, v66
	v_fmac_f32_e32 v237, v67, v67
	v_mov_b32_e32 v238, v237
	s_nop 1
	v_permlane16_swap_b32_e32 v237, v238
	v_add_f32_e32 v237, v237, v238
	v_mov_b32_e32 v238, v237
	s_nop 1
	v_permlane32_swap_b32_e32 v237, v238
	v_add_f32_e32 v237, v237, v238
	global_store_dword v241, v237, s[66:67]
	v_add_u32_e32 v239, 0x80000, v234
	v_add_u32_e32 v240, 0x40000, v235
	v_add_u32_e32 v241, 0x2000, v236
	s_waitcnt vmcnt(42)
	v_fma_f32 v60, v60, 0.5, v144
	v_fma_f32 v61, v61, 0.5, v145
	v_fma_f32 v62, v62, 0.5, v146
	v_fma_f32 v63, v63, 0.5, v147
	v_fma_f32 v56, v56, 0.5, v156
	v_fma_f32 v57, v57, 0.5, v157
	v_fma_f32 v58, v58, 0.5, v158
	v_fma_f32 v59, v59, 0.5, v159
	global_store_dwordx4 v239, v[60:63], s[68:69]
	global_store_dwordx4 v239, v[56:59], s[68:69] offset:16
	v_cvt_pk_bf16_f32 v244, v60, v61
	v_cvt_pk_bf16_f32 v245, v62, v63
	v_cvt_pk_bf16_f32 v246, v56, v57
	v_cvt_pk_bf16_f32 v247, v58, v59
	global_store_dwordx4 v240, v[244:247], s[66:67]
	v_mul_f32_e32 v237, v60, v60
	v_fmac_f32_e32 v237, v61, v61
	v_fmac_f32_e32 v237, v62, v62
	v_fmac_f32_e32 v237, v63, v63
	v_fmac_f32_e32 v237, v56, v56
	v_fmac_f32_e32 v237, v57, v57
	v_fmac_f32_e32 v237, v58, v58
	v_fmac_f32_e32 v237, v59, v59
	s_waitcnt vmcnt(40)
	v_fma_f32 v52, v52, 0.5, v160
	v_fma_f32 v53, v53, 0.5, v161
	v_fma_f32 v54, v54, 0.5, v162
	v_fma_f32 v55, v55, 0.5, v163
	v_fma_f32 v48, v48, 0.5, v164
	v_fma_f32 v49, v49, 0.5, v165
	v_fma_f32 v50, v50, 0.5, v166
	v_fma_f32 v51, v51, 0.5, v167
	global_store_dwordx4 v239, v[52:55], s[68:69] offset:512
	global_store_dwordx4 v239, v[48:51], s[68:69] offset:528
	v_cvt_pk_bf16_f32 v248, v52, v53
	v_cvt_pk_bf16_f32 v249, v54, v55
	v_cvt_pk_bf16_f32 v250, v48, v49
	v_cvt_pk_bf16_f32 v251, v50, v51
	global_store_dwordx4 v240, v[248:251], s[66:67] offset:256
	v_fmac_f32_e32 v237, v52, v52
	v_fmac_f32_e32 v237, v53, v53
	v_fmac_f32_e32 v237, v54, v54
	v_fmac_f32_e32 v237, v55, v55
	v_fmac_f32_e32 v237, v48, v48
	v_fmac_f32_e32 v237, v49, v49
	v_fmac_f32_e32 v237, v50, v50
	v_fmac_f32_e32 v237, v51, v51
	v_mov_b32_e32 v238, v237
	s_nop 1
	v_permlane16_swap_b32_e32 v237, v238
	v_add_f32_e32 v237, v237, v238
	v_mov_b32_e32 v238, v237
	s_nop 1
	v_permlane32_swap_b32_e32 v237, v238
	v_add_f32_e32 v237, v237, v238
	global_store_dword v241, v237, s[66:67]
	v_add_u32_e32 v239, 0x90000, v234
	v_add_u32_e32 v240, 0x48000, v235
	v_add_u32_e32 v241, 0x2400, v236
	s_waitcnt vmcnt(38)
	v_fma_f32 v44, v44, 0.5, v168
	v_fma_f32 v45, v45, 0.5, v169
	v_fma_f32 v46, v46, 0.5, v170
	v_fma_f32 v47, v47, 0.5, v171
	v_fma_f32 v40, v40, 0.5, v172
	v_fma_f32 v41, v41, 0.5, v173
	v_fma_f32 v42, v42, 0.5, v174
	v_fma_f32 v43, v43, 0.5, v175
	global_store_dwordx4 v239, v[44:47], s[68:69]
	global_store_dwordx4 v239, v[40:43], s[68:69] offset:16
	v_cvt_pk_bf16_f32 v244, v44, v45
	v_cvt_pk_bf16_f32 v245, v46, v47
	v_cvt_pk_bf16_f32 v246, v40, v41
	v_cvt_pk_bf16_f32 v247, v42, v43
	global_store_dwordx4 v240, v[244:247], s[66:67]
	v_mul_f32_e32 v237, v44, v44
	v_fmac_f32_e32 v237, v45, v45
	v_fmac_f32_e32 v237, v46, v46
	v_fmac_f32_e32 v237, v47, v47
	v_fmac_f32_e32 v237, v40, v40
	v_fmac_f32_e32 v237, v41, v41
	v_fmac_f32_e32 v237, v42, v42
	v_fmac_f32_e32 v237, v43, v43
	s_waitcnt vmcnt(36)
	v_fma_f32 v36, v36, 0.5, v176
	v_fma_f32 v37, v37, 0.5, v177
	v_fma_f32 v38, v38, 0.5, v178
	v_fma_f32 v39, v39, 0.5, v179
	v_fma_f32 v32, v32, 0.5, v180
	v_fma_f32 v33, v33, 0.5, v181
	v_fma_f32 v34, v34, 0.5, v182
	v_fma_f32 v35, v35, 0.5, v183
	global_store_dwordx4 v239, v[36:39], s[68:69] offset:512
	global_store_dwordx4 v239, v[32:35], s[68:69] offset:528
	v_cvt_pk_bf16_f32 v248, v36, v37
	v_cvt_pk_bf16_f32 v249, v38, v39
	v_cvt_pk_bf16_f32 v250, v32, v33
	v_cvt_pk_bf16_f32 v251, v34, v35
	global_store_dwordx4 v240, v[248:251], s[66:67] offset:256
	v_fmac_f32_e32 v237, v36, v36
	v_fmac_f32_e32 v237, v37, v37
	v_fmac_f32_e32 v237, v38, v38
	v_fmac_f32_e32 v237, v39, v39
	v_fmac_f32_e32 v237, v32, v32
	v_fmac_f32_e32 v237, v33, v33
	v_fmac_f32_e32 v237, v34, v34
	v_fmac_f32_e32 v237, v35, v35
	v_mov_b32_e32 v238, v237
	s_nop 1
	v_permlane16_swap_b32_e32 v237, v238
	v_add_f32_e32 v237, v237, v238
	v_mov_b32_e32 v238, v237
	s_nop 1
	v_permlane32_swap_b32_e32 v237, v238
	v_add_f32_e32 v237, v237, v238
	global_store_dword v241, v237, s[66:67]
	v_add_u32_e32 v239, 0xa0000, v234
	v_add_u32_e32 v240, 0x50000, v235
	v_add_u32_e32 v241, 0x2800, v236
	s_waitcnt vmcnt(34)
	v_fma_f32 v28, v28, 0.5, v184
	v_fma_f32 v29, v29, 0.5, v185
	v_fma_f32 v30, v30, 0.5, v186
	v_fma_f32 v31, v31, 0.5, v187
	v_fma_f32 v24, v24, 0.5, v188
	v_fma_f32 v25, v25, 0.5, v189
	v_fma_f32 v26, v26, 0.5, v190
	v_fma_f32 v27, v27, 0.5, v191
	global_store_dwordx4 v239, v[28:31], s[68:69]
	global_store_dwordx4 v239, v[24:27], s[68:69] offset:16
	v_cvt_pk_bf16_f32 v244, v28, v29
	v_cvt_pk_bf16_f32 v245, v30, v31
	v_cvt_pk_bf16_f32 v246, v24, v25
	v_cvt_pk_bf16_f32 v247, v26, v27
	global_store_dwordx4 v240, v[244:247], s[66:67]
	v_mul_f32_e32 v237, v28, v28
	v_fmac_f32_e32 v237, v29, v29
	v_fmac_f32_e32 v237, v30, v30
	v_fmac_f32_e32 v237, v31, v31
	v_fmac_f32_e32 v237, v24, v24
	v_fmac_f32_e32 v237, v25, v25
	v_fmac_f32_e32 v237, v26, v26
	v_fmac_f32_e32 v237, v27, v27
	s_waitcnt vmcnt(32)
	v_fma_f32 v20, v20, 0.5, v196
	v_fma_f32 v21, v21, 0.5, v197
	v_fma_f32 v22, v22, 0.5, v198
	v_fma_f32 v23, v23, 0.5, v199
	v_fma_f32 v16, v16, 0.5, v200
	v_fma_f32 v17, v17, 0.5, v201
	v_fma_f32 v18, v18, 0.5, v202
	v_fma_f32 v19, v19, 0.5, v203
	global_store_dwordx4 v239, v[20:23], s[68:69] offset:512
	global_store_dwordx4 v239, v[16:19], s[68:69] offset:528
	v_cvt_pk_bf16_f32 v248, v20, v21
	v_cvt_pk_bf16_f32 v249, v22, v23
	v_cvt_pk_bf16_f32 v250, v16, v17
	v_cvt_pk_bf16_f32 v251, v18, v19
	global_store_dwordx4 v240, v[248:251], s[66:67] offset:256
	v_fmac_f32_e32 v237, v20, v20
	v_fmac_f32_e32 v237, v21, v21
	v_fmac_f32_e32 v237, v22, v22
	v_fmac_f32_e32 v237, v23, v23
	v_fmac_f32_e32 v237, v16, v16
	v_fmac_f32_e32 v237, v17, v17
	v_fmac_f32_e32 v237, v18, v18
	v_fmac_f32_e32 v237, v19, v19
	v_mov_b32_e32 v238, v237
	s_nop 1
	v_permlane16_swap_b32_e32 v237, v238
	v_add_f32_e32 v237, v237, v238
	v_mov_b32_e32 v238, v237
	s_nop 1
	v_permlane32_swap_b32_e32 v237, v238
	v_add_f32_e32 v237, v237, v238
	global_store_dword v241, v237, s[66:67]
	v_add_u32_e32 v239, 0xb0000, v234
	v_add_u32_e32 v240, 0x58000, v235
	v_add_u32_e32 v241, 0x2c00, v236
	s_waitcnt vmcnt(30)
	v_fma_f32 v12, v12, 0.5, v204
	v_fma_f32 v13, v13, 0.5, v205
	v_fma_f32 v14, v14, 0.5, v206
	v_fma_f32 v15, v15, 0.5, v207
	v_fma_f32 v8, v8, 0.5, v208
	v_fma_f32 v9, v9, 0.5, v209
	v_fma_f32 v10, v10, 0.5, v210
	v_fma_f32 v11, v11, 0.5, v211
	global_store_dwordx4 v239, v[12:15], s[68:69]
	global_store_dwordx4 v239, v[8:11], s[68:69] offset:16
	v_cvt_pk_bf16_f32 v244, v12, v13
	v_cvt_pk_bf16_f32 v245, v14, v15
	v_cvt_pk_bf16_f32 v246, v8, v9
	v_cvt_pk_bf16_f32 v247, v10, v11
	global_store_dwordx4 v240, v[244:247], s[66:67]
	v_mul_f32_e32 v237, v12, v12
	v_fmac_f32_e32 v237, v13, v13
	v_fmac_f32_e32 v237, v14, v14
	v_fmac_f32_e32 v237, v15, v15
	v_fmac_f32_e32 v237, v8, v8
	v_fmac_f32_e32 v237, v9, v9
	v_fmac_f32_e32 v237, v10, v10
	v_fmac_f32_e32 v237, v11, v11
	s_waitcnt vmcnt(28)
	v_fma_f32 v4, v4, 0.5, v212
	v_fma_f32 v5, v5, 0.5, v213
	v_fma_f32 v6, v6, 0.5, v214
	v_fma_f32 v7, v7, 0.5, v215
	v_fma_f32 v0, v0, 0.5, v216
	v_fma_f32 v1, v1, 0.5, v217
	v_fma_f32 v2, v2, 0.5, v218
	v_fma_f32 v3, v3, 0.5, v219
	global_store_dwordx4 v239, v[4:7], s[68:69] offset:512
	global_store_dwordx4 v239, v[0:3], s[68:69] offset:528
	v_cvt_pk_bf16_f32 v248, v4, v5
	v_cvt_pk_bf16_f32 v249, v6, v7
	v_cvt_pk_bf16_f32 v250, v0, v1
	v_cvt_pk_bf16_f32 v251, v2, v3
	global_store_dwordx4 v240, v[248:251], s[66:67] offset:256
	v_fmac_f32_e32 v237, v4, v4
	v_fmac_f32_e32 v237, v5, v5
	v_fmac_f32_e32 v237, v6, v6
	v_fmac_f32_e32 v237, v7, v7
	v_fmac_f32_e32 v237, v0, v0
	v_fmac_f32_e32 v237, v1, v1
	v_fmac_f32_e32 v237, v2, v2
	v_fmac_f32_e32 v237, v3, v3
	v_mov_b32_e32 v238, v237
	s_nop 1
	v_permlane16_swap_b32_e32 v237, v238
	v_add_f32_e32 v237, v237, v238
	v_mov_b32_e32 v238, v237
	s_nop 1
	v_permlane32_swap_b32_e32 v237, v238
	v_add_f32_e32 v237, v237, v238
	global_store_dword v241, v237, s[66:67]
	s_and_b64 vcc, exec, s[16:17]
	s_mov_b64 s[16:17], -1
	s_cbranch_vccnz .LBB0_1779
	s_andn2_b64 vcc, exec, s[22:23]
	s_cbranch_vccnz .LBB0_1778
	s_barrier
	s_branch .LBB0_1778

.LBB0_2145:
	v_and_b32_e32 v252, 63, v194
	v_lshrrev_b32_e32 v253, 6, v194
	v_and_b32_e32 v254, 15, v252
	v_lshrrev_b32_e32 v255, 4, v252
	v_lshrrev_b32_e32 v252, 2, v253
	v_and_b32_e32 v253, 3, v253
	v_lshl_add_u32 v252, v252, 6, v254
	s_lshl_b32 s98, s80, 8
	v_add_u32_e32 v252, s98, v252
	v_lshlrev_b32_e32 v255, 3, v255
	v_lshl_add_u32 v255, v253, 5, v255
	s_lshl_b32 s98, s20, 8
	v_add_u32_e32 v255, s98, v255
	v_lshlrev_b32_e32 v234, 12, v252
	v_lshl_add_u32 v234, v255, 2, v234
	v_lshlrev_b32_e32 v235, 11, v252
	v_lshl_add_u32 v235, v255, 1, v235
	v_add_u32_e32 v235, 0x3800000, v235
	v_lshlrev_b32_e32 v236, 6, v252
	v_lshl_add_u32 v236, v253, 2, v236
	s_lshl_b32 s98, s20, 4
	s_add_i32 s98, s98, 0x3600000
	v_add_u32_e32 v236, s98, v236
	v_mov_b32_e32 v242, v234
	global_load_dwordx4 v[144:147], v242, s[68:69]
	global_load_dwordx4 v[156:159], v242, s[68:69] offset:16
	v_mov_b32_e32 v242, v234
	global_load_dwordx4 v[160:163], v242, s[68:69] offset:512
	global_load_dwordx4 v[164:167], v242, s[68:69] offset:528
	v_add_u32_e32 v242, 0x10000, v234
	global_load_dwordx4 v[168:171], v242, s[68:69]
	global_load_dwordx4 v[172:175], v242, s[68:69] offset:16
	v_add_u32_e32 v242, 0x10000, v234
	global_load_dwordx4 v[176:179], v242, s[68:69] offset:512
	global_load_dwordx4 v[180:183], v242, s[68:69] offset:528
	v_add_u32_e32 v242, 0x20000, v234
	global_load_dwordx4 v[184:187], v242, s[68:69]
	global_load_dwordx4 v[188:191], v242, s[68:69] offset:16
	v_add_u32_e32 v242, 0x20000, v234
	global_load_dwordx4 v[196:199], v242, s[68:69] offset:512
	global_load_dwordx4 v[200:203], v242, s[68:69] offset:528
	v_add_u32_e32 v242, 0x30000, v234
	global_load_dwordx4 v[204:207], v242, s[68:69]
	global_load_dwordx4 v[208:211], v242, s[68:69] offset:16
	v_add_u32_e32 v242, 0x30000, v234
	global_load_dwordx4 v[212:215], v242, s[68:69] offset:512
	global_load_dwordx4 v[216:219], v242, s[68:69] offset:528
	v_mov_b32_e32 v239, v234
	v_mov_b32_e32 v240, v235
	v_mov_b32_e32 v241, v236
	s_waitcnt vmcnt(14)
	v_fma_f32 v124, v124, 0.5, v144
	v_fma_f32 v125, v125, 0.5, v145
	v_fma_f32 v126, v126, 0.5, v146
	v_fma_f32 v127, v127, 0.5, v147
	v_fma_f32 v120, v120, 0.5, v156
	v_fma_f32 v121, v121, 0.5, v157
	v_fma_f32 v122, v122, 0.5, v158
	v_fma_f32 v123, v123, 0.5, v159
	v_add_u32_e32 v242, 0x80000, v234
	global_load_dwordx4 v[144:147], v242, s[68:69]
	global_load_dwordx4 v[156:159], v242, s[68:69] offset:16
	global_store_dwordx4 v239, v[124:127], s[68:69]
	global_store_dwordx4 v239, v[120:123], s[68:69] offset:16
	v_cvt_pk_bf16_f32 v244, v124, v125
	v_cvt_pk_bf16_f32 v245, v126, v127
	v_cvt_pk_bf16_f32 v246, v120, v121
	v_cvt_pk_bf16_f32 v247, v122, v123
	global_store_dwordx4 v240, v[244:247], s[66:67]
	v_mul_f32_e32 v237, v124, v124
	v_fmac_f32_e32 v237, v125, v125
	v_fmac_f32_e32 v237, v126, v126
	v_fmac_f32_e32 v237, v127, v127
	v_fmac_f32_e32 v237, v120, v120
	v_fmac_f32_e32 v237, v121, v121
	v_fmac_f32_e32 v237, v122, v122
	v_fmac_f32_e32 v237, v123, v123
	s_waitcnt vmcnt(17)
	v_fma_f32 v116, v116, 0.5, v160
	v_fma_f32 v117, v117, 0.5, v161
	v_fma_f32 v118, v118, 0.5, v162
	v_fma_f32 v119, v119, 0.5, v163
	v_fma_f32 v112, v112, 0.5, v164
	v_fma_f32 v113, v113, 0.5, v165
	v_fma_f32 v114, v114, 0.5, v166
	v_fma_f32 v115, v115, 0.5, v167
	v_add_u32_e32 v242, 0x80000, v234
	global_load_dwordx4 v[160:163], v242, s[68:69] offset:512
	global_load_dwordx4 v[164:167], v242, s[68:69] offset:528
	global_store_dwordx4 v239, v[116:119], s[68:69] offset:512
	global_store_dwordx4 v239, v[112:115], s[68:69] offset:528
	v_cvt_pk_bf16_f32 v248, v116, v117
	v_cvt_pk_bf16_f32 v249, v118, v119
	v_cvt_pk_bf16_f32 v250, v112, v113
	v_cvt_pk_bf16_f32 v251, v114, v115
	global_store_dwordx4 v240, v[248:251], s[66:67] offset:256
	v_fmac_f32_e32 v237, v116, v116
	v_fmac_f32_e32 v237, v117, v117
	v_fmac_f32_e32 v237, v118, v118
	v_fmac_f32_e32 v237, v119, v119
	v_fmac_f32_e32 v237, v112, v112
	v_fmac_f32_e32 v237, v113, v113
	v_fmac_f32_e32 v237, v114, v114
	v_fmac_f32_e32 v237, v115, v115
	v_mov_b32_e32 v238, v237
	s_nop 1
	v_permlane16_swap_b32_e32 v237, v238
	v_add_f32_e32 v237, v237, v238
	v_mov_b32_e32 v238, v237
	s_nop 1
	v_permlane32_swap_b32_e32 v237, v238
	v_add_f32_e32 v237, v237, v238
	global_store_dword v241, v237, s[66:67]
	v_add_u32_e32 v239, 0x10000, v234
	v_add_u32_e32 v240, 0x8000, v235
	v_add_u32_e32 v241, 0x400, v236
	s_waitcnt vmcnt(21)
	v_fma_f32 v108, v108, 0.5, v168
	v_fma_f32 v109, v109, 0.5, v169
	v_fma_f32 v110, v110, 0.5, v170
	v_fma_f32 v111, v111, 0.5, v171
	v_fma_f32 v104, v104, 0.5, v172
	v_fma_f32 v105, v105, 0.5, v173
	v_fma_f32 v106, v106, 0.5, v174
	v_fma_f32 v107, v107, 0.5, v175
	v_add_u32_e32 v242, 0x90000, v234
	global_load_dwordx4 v[168:171], v242, s[68:69]
	global_load_dwordx4 v[172:175], v242, s[68:69] offset:16
	global_store_dwordx4 v239, v[108:111], s[68:69]
	global_store_dwordx4 v239, v[104:107], s[68:69] offset:16
	v_cvt_pk_bf16_f32 v244, v108, v109
	v_cvt_pk_bf16_f32 v245, v110, v111
	v_cvt_pk_bf16_f32 v246, v104, v105
	v_cvt_pk_bf16_f32 v247, v106, v107
	global_store_dwordx4 v240, v[244:247], s[66:67]
	v_mul_f32_e32 v237, v108, v108
	v_fmac_f32_e32 v237, v109, v109
	v_fmac_f32_e32 v237, v110, v110
	v_fmac_f32_e32 v237, v111, v111
	v_fmac_f32_e32 v237, v104, v104
	v_fmac_f32_e32 v237, v105, v105
	v_fmac_f32_e32 v237, v106, v106
	v_fmac_f32_e32 v237, v107, v107
	s_waitcnt vmcnt(24)
	v_fma_f32 v100, v100, 0.5, v176
	v_fma_f32 v101, v101, 0.5, v177
	v_fma_f32 v102, v102, 0.5, v178
	v_fma_f32 v103, v103, 0.5, v179
	v_fma_f32 v96, v96, 0.5, v180
	v_fma_f32 v97, v97, 0.5, v181
	v_fma_f32 v98, v98, 0.5, v182
	v_fma_f32 v99, v99, 0.5, v183
	v_add_u32_e32 v242, 0x90000, v234
	global_load_dwordx4 v[176:179], v242, s[68:69] offset:512
	global_load_dwordx4 v[180:183], v242, s[68:69] offset:528
	global_store_dwordx4 v239, v[100:103], s[68:69] offset:512
	global_store_dwordx4 v239, v[96:99], s[68:69] offset:528
	v_cvt_pk_bf16_f32 v248, v100, v101
	v_cvt_pk_bf16_f32 v249, v102, v103
	v_cvt_pk_bf16_f32 v250, v96, v97
	v_cvt_pk_bf16_f32 v251, v98, v99
	global_store_dwordx4 v240, v[248:251], s[66:67] offset:256
	v_fmac_f32_e32 v237, v100, v100
	v_fmac_f32_e32 v237, v101, v101
	v_fmac_f32_e32 v237, v102, v102
	v_fmac_f32_e32 v237, v103, v103
	v_fmac_f32_e32 v237, v96, v96
	v_fmac_f32_e32 v237, v97, v97
	v_fmac_f32_e32 v237, v98, v98
	v_fmac_f32_e32 v237, v99, v99
	v_mov_b32_e32 v238, v237
	s_nop 1
	v_permlane16_swap_b32_e32 v237, v238
	v_add_f32_e32 v237, v237, v238
	v_mov_b32_e32 v238, v237
	s_nop 1
	v_permlane32_swap_b32_e32 v237, v238
	v_add_f32_e32 v237, v237, v238
	global_store_dword v241, v237, s[66:67]
	v_add_u32_e32 v239, 0x20000, v234
	v_add_u32_e32 v240, 0x10000, v235
	v_add_u32_e32 v241, 0x800, v236
	s_waitcnt vmcnt(28)
	v_fma_f32 v92, v92, 0.5, v184
	v_fma_f32 v93, v93, 0.5, v185
	v_fma_f32 v94, v94, 0.5, v186
	v_fma_f32 v95, v95, 0.5, v187
	v_fma_f32 v88, v88, 0.5, v188
	v_fma_f32 v89, v89, 0.5, v189
	v_fma_f32 v90, v90, 0.5, v190
	v_fma_f32 v91, v91, 0.5, v191
	v_add_u32_e32 v242, 0xa0000, v234
	global_load_dwordx4 v[184:187], v242, s[68:69]
	global_load_dwordx4 v[188:191], v242, s[68:69] offset:16
	global_store_dwordx4 v239, v[92:95], s[68:69]
	global_store_dwordx4 v239, v[88:91], s[68:69] offset:16
	v_cvt_pk_bf16_f32 v244, v92, v93
	v_cvt_pk_bf16_f32 v245, v94, v95
	v_cvt_pk_bf16_f32 v246, v88, v89
	v_cvt_pk_bf16_f32 v247, v90, v91
	global_store_dwordx4 v240, v[244:247], s[66:67]
	v_mul_f32_e32 v237, v92, v92
	v_fmac_f32_e32 v237, v93, v93
	v_fmac_f32_e32 v237, v94, v94
	v_fmac_f32_e32 v237, v95, v95
	v_fmac_f32_e32 v237, v88, v88
	v_fmac_f32_e32 v237, v89, v89
	v_fmac_f32_e32 v237, v90, v90
	v_fmac_f32_e32 v237, v91, v91
	s_waitcnt vmcnt(31)
	v_fma_f32 v84, v84, 0.5, v196
	v_fma_f32 v85, v85, 0.5, v197
	v_fma_f32 v86, v86, 0.5, v198
	v_fma_f32 v87, v87, 0.5, v199
	v_fma_f32 v80, v80, 0.5, v200
	v_fma_f32 v81, v81, 0.5, v201
	v_fma_f32 v82, v82, 0.5, v202
	v_fma_f32 v83, v83, 0.5, v203
	v_add_u32_e32 v242, 0xa0000, v234
	global_load_dwordx4 v[196:199], v242, s[68:69] offset:512
	global_load_dwordx4 v[200:203], v242, s[68:69] offset:528
	global_store_dwordx4 v239, v[84:87], s[68:69] offset:512
	global_store_dwordx4 v239, v[80:83], s[68:69] offset:528
	v_cvt_pk_bf16_f32 v248, v84, v85
	v_cvt_pk_bf16_f32 v249, v86, v87
	v_cvt_pk_bf16_f32 v250, v80, v81
	v_cvt_pk_bf16_f32 v251, v82, v83
	global_store_dwordx4 v240, v[248:251], s[66:67] offset:256
	v_fmac_f32_e32 v237, v84, v84
	v_fmac_f32_e32 v237, v85, v85
	v_fmac_f32_e32 v237, v86, v86
	v_fmac_f32_e32 v237, v87, v87
	v_fmac_f32_e32 v237, v80, v80
	v_fmac_f32_e32 v237, v81, v81
	v_fmac_f32_e32 v237, v82, v82
	v_fmac_f32_e32 v237, v83, v83
	v_mov_b32_e32 v238, v237
	s_nop 1
	v_permlane16_swap_b32_e32 v237, v238
	v_add_f32_e32 v237, v237, v238
	v_mov_b32_e32 v238, v237
	s_nop 1
	v_permlane32_swap_b32_e32 v237, v238
	v_add_f32_e32 v237, v237, v238
	global_store_dword v241, v237, s[66:67]
	v_add_u32_e32 v239, 0x30000, v234
	v_add_u32_e32 v240, 0x18000, v235
	v_add_u32_e32 v241, 0xc00, v236
	s_waitcnt vmcnt(35)
	v_fma_f32 v76, v76, 0.5, v204
	v_fma_f32 v77, v77, 0.5, v205
	v_fma_f32 v78, v78, 0.5, v206
	v_fma_f32 v79, v79, 0.5, v207
	v_fma_f32 v72, v72, 0.5, v208
	v_fma_f32 v73, v73, 0.5, v209
	v_fma_f32 v74, v74, 0.5, v210
	v_fma_f32 v75, v75, 0.5, v211
	v_add_u32_e32 v242, 0xb0000, v234
	global_load_dwordx4 v[204:207], v242, s[68:69]
	global_load_dwordx4 v[208:211], v242, s[68:69] offset:16
	global_store_dwordx4 v239, v[76:79], s[68:69]
	global_store_dwordx4 v239, v[72:75], s[68:69] offset:16
	v_cvt_pk_bf16_f32 v244, v76, v77
	v_cvt_pk_bf16_f32 v245, v78, v79
	v_cvt_pk_bf16_f32 v246, v72, v73
	v_cvt_pk_bf16_f32 v247, v74, v75
	global_store_dwordx4 v240, v[244:247], s[66:67]
	v_mul_f32_e32 v237, v76, v76
	v_fmac_f32_e32 v237, v77, v77
	v_fmac_f32_e32 v237, v78, v78
	v_fmac_f32_e32 v237, v79, v79
	v_fmac_f32_e32 v237, v72, v72
	v_fmac_f32_e32 v237, v73, v73
	v_fmac_f32_e32 v237, v74, v74
	v_fmac_f32_e32 v237, v75, v75
	s_waitcnt vmcnt(38)
	v_fma_f32 v68, v68, 0.5, v212
	v_fma_f32 v69, v69, 0.5, v213
	v_fma_f32 v70, v70, 0.5, v214
	v_fma_f32 v71, v71, 0.5, v215
	v_fma_f32 v64, v64, 0.5, v216
	v_fma_f32 v65, v65, 0.5, v217
	v_fma_f32 v66, v66, 0.5, v218
	v_fma_f32 v67, v67, 0.5, v219
	v_add_u32_e32 v242, 0xb0000, v234
	global_load_dwordx4 v[212:215], v242, s[68:69] offset:512
	global_load_dwordx4 v[216:219], v242, s[68:69] offset:528
	global_store_dwordx4 v239, v[68:71], s[68:69] offset:512
	global_store_dwordx4 v239, v[64:67], s[68:69] offset:528
	v_cvt_pk_bf16_f32 v248, v68, v69
	v_cvt_pk_bf16_f32 v249, v70, v71
	v_cvt_pk_bf16_f32 v250, v64, v65
	v_cvt_pk_bf16_f32 v251, v66, v67
	global_store_dwordx4 v240, v[248:251], s[66:67] offset:256
	v_fmac_f32_e32 v237, v68, v68
	v_fmac_f32_e32 v237, v69, v69
	v_fmac_f32_e32 v237, v70, v70
	v_fmac_f32_e32 v237, v71, v71
	v_fmac_f32_e32 v237, v64, v64
	v_fmac_f32_e32 v237, v65, v65
	v_fmac_f32_e32 v237, v66, v66
	v_fmac_f32_e32 v237, v67, v67
	v_mov_b32_e32 v238, v237
	s_nop 1
	v_permlane16_swap_b32_e32 v237, v238
	v_add_f32_e32 v237, v237, v238
	v_mov_b32_e32 v238, v237
	s_nop 1
	v_permlane32_swap_b32_e32 v237, v238
	v_add_f32_e32 v237, v237, v238
	global_store_dword v241, v237, s[66:67]
	v_add_u32_e32 v239, 0x80000, v234
	v_add_u32_e32 v240, 0x40000, v235
	v_add_u32_e32 v241, 0x2000, v236
	s_waitcnt vmcnt(42)
	v_fma_f32 v60, v60, 0.5, v144
	v_fma_f32 v61, v61, 0.5, v145
	v_fma_f32 v62, v62, 0.5, v146
	v_fma_f32 v63, v63, 0.5, v147
	v_fma_f32 v56, v56, 0.5, v156
	v_fma_f32 v57, v57, 0.5, v157
	v_fma_f32 v58, v58, 0.5, v158
	v_fma_f32 v59, v59, 0.5, v159
	global_store_dwordx4 v239, v[60:63], s[68:69]
	global_store_dwordx4 v239, v[56:59], s[68:69] offset:16
	v_cvt_pk_bf16_f32 v244, v60, v61
	v_cvt_pk_bf16_f32 v245, v62, v63
	v_cvt_pk_bf16_f32 v246, v56, v57
	v_cvt_pk_bf16_f32 v247, v58, v59
	global_store_dwordx4 v240, v[244:247], s[66:67]
	v_mul_f32_e32 v237, v60, v60
	v_fmac_f32_e32 v237, v61, v61
	v_fmac_f32_e32 v237, v62, v62
	v_fmac_f32_e32 v237, v63, v63
	v_fmac_f32_e32 v237, v56, v56
	v_fmac_f32_e32 v237, v57, v57
	v_fmac_f32_e32 v237, v58, v58
	v_fmac_f32_e32 v237, v59, v59
	s_waitcnt vmcnt(40)
	v_fma_f32 v52, v52, 0.5, v160
	v_fma_f32 v53, v53, 0.5, v161
	v_fma_f32 v54, v54, 0.5, v162
	v_fma_f32 v55, v55, 0.5, v163
	v_fma_f32 v48, v48, 0.5, v164
	v_fma_f32 v49, v49, 0.5, v165
	v_fma_f32 v50, v50, 0.5, v166
	v_fma_f32 v51, v51, 0.5, v167
	global_store_dwordx4 v239, v[52:55], s[68:69] offset:512
	global_store_dwordx4 v239, v[48:51], s[68:69] offset:528
	v_cvt_pk_bf16_f32 v248, v52, v53
	v_cvt_pk_bf16_f32 v249, v54, v55
	v_cvt_pk_bf16_f32 v250, v48, v49
	v_cvt_pk_bf16_f32 v251, v50, v51
	global_store_dwordx4 v240, v[248:251], s[66:67] offset:256
	v_fmac_f32_e32 v237, v52, v52
	v_fmac_f32_e32 v237, v53, v53
	v_fmac_f32_e32 v237, v54, v54
	v_fmac_f32_e32 v237, v55, v55
	v_fmac_f32_e32 v237, v48, v48
	v_fmac_f32_e32 v237, v49, v49
	v_fmac_f32_e32 v237, v50, v50
	v_fmac_f32_e32 v237, v51, v51
	v_mov_b32_e32 v238, v237
	s_nop 1
	v_permlane16_swap_b32_e32 v237, v238
	v_add_f32_e32 v237, v237, v238
	v_mov_b32_e32 v238, v237
	s_nop 1
	v_permlane32_swap_b32_e32 v237, v238
	v_add_f32_e32 v237, v237, v238
	global_store_dword v241, v237, s[66:67]
	v_add_u32_e32 v239, 0x90000, v234
	v_add_u32_e32 v240, 0x48000, v235
	v_add_u32_e32 v241, 0x2400, v236
	s_waitcnt vmcnt(38)
	v_fma_f32 v44, v44, 0.5, v168
	v_fma_f32 v45, v45, 0.5, v169
	v_fma_f32 v46, v46, 0.5, v170
	v_fma_f32 v47, v47, 0.5, v171
	v_fma_f32 v40, v40, 0.5, v172
	v_fma_f32 v41, v41, 0.5, v173
	v_fma_f32 v42, v42, 0.5, v174
	v_fma_f32 v43, v43, 0.5, v175
	global_store_dwordx4 v239, v[44:47], s[68:69]
	global_store_dwordx4 v239, v[40:43], s[68:69] offset:16
	v_cvt_pk_bf16_f32 v244, v44, v45
	v_cvt_pk_bf16_f32 v245, v46, v47
	v_cvt_pk_bf16_f32 v246, v40, v41
	v_cvt_pk_bf16_f32 v247, v42, v43
	global_store_dwordx4 v240, v[244:247], s[66:67]
	v_mul_f32_e32 v237, v44, v44
	v_fmac_f32_e32 v237, v45, v45
	v_fmac_f32_e32 v237, v46, v46
	v_fmac_f32_e32 v237, v47, v47
	v_fmac_f32_e32 v237, v40, v40
	v_fmac_f32_e32 v237, v41, v41
	v_fmac_f32_e32 v237, v42, v42
	v_fmac_f32_e32 v237, v43, v43
	s_waitcnt vmcnt(36)
	v_fma_f32 v36, v36, 0.5, v176
	v_fma_f32 v37, v37, 0.5, v177
	v_fma_f32 v38, v38, 0.5, v178
	v_fma_f32 v39, v39, 0.5, v179
	v_fma_f32 v32, v32, 0.5, v180
	v_fma_f32 v33, v33, 0.5, v181
	v_fma_f32 v34, v34, 0.5, v182
	v_fma_f32 v35, v35, 0.5, v183
	global_store_dwordx4 v239, v[36:39], s[68:69] offset:512
	global_store_dwordx4 v239, v[32:35], s[68:69] offset:528
	v_cvt_pk_bf16_f32 v248, v36, v37
	v_cvt_pk_bf16_f32 v249, v38, v39
	v_cvt_pk_bf16_f32 v250, v32, v33
	v_cvt_pk_bf16_f32 v251, v34, v35
	global_store_dwordx4 v240, v[248:251], s[66:67] offset:256
	v_fmac_f32_e32 v237, v36, v36
	v_fmac_f32_e32 v237, v37, v37
	v_fmac_f32_e32 v237, v38, v38
	v_fmac_f32_e32 v237, v39, v39
	v_fmac_f32_e32 v237, v32, v32
	v_fmac_f32_e32 v237, v33, v33
	v_fmac_f32_e32 v237, v34, v34
	v_fmac_f32_e32 v237, v35, v35
	v_mov_b32_e32 v238, v237
	s_nop 1
	v_permlane16_swap_b32_e32 v237, v238
	v_add_f32_e32 v237, v237, v238
	v_mov_b32_e32 v238, v237
	s_nop 1
	v_permlane32_swap_b32_e32 v237, v238
	v_add_f32_e32 v237, v237, v238
	global_store_dword v241, v237, s[66:67]
	v_add_u32_e32 v239, 0xa0000, v234
	v_add_u32_e32 v240, 0x50000, v235
	v_add_u32_e32 v241, 0x2800, v236
	s_waitcnt vmcnt(34)
	v_fma_f32 v28, v28, 0.5, v184
	v_fma_f32 v29, v29, 0.5, v185
	v_fma_f32 v30, v30, 0.5, v186
	v_fma_f32 v31, v31, 0.5, v187
	v_fma_f32 v24, v24, 0.5, v188
	v_fma_f32 v25, v25, 0.5, v189
	v_fma_f32 v26, v26, 0.5, v190
	v_fma_f32 v27, v27, 0.5, v191
	global_store_dwordx4 v239, v[28:31], s[68:69]
	global_store_dwordx4 v239, v[24:27], s[68:69] offset:16
	v_cvt_pk_bf16_f32 v244, v28, v29
	v_cvt_pk_bf16_f32 v245, v30, v31
	v_cvt_pk_bf16_f32 v246, v24, v25
	v_cvt_pk_bf16_f32 v247, v26, v27
	global_store_dwordx4 v240, v[244:247], s[66:67]
	v_mul_f32_e32 v237, v28, v28
	v_fmac_f32_e32 v237, v29, v29
	v_fmac_f32_e32 v237, v30, v30
	v_fmac_f32_e32 v237, v31, v31
	v_fmac_f32_e32 v237, v24, v24
	v_fmac_f32_e32 v237, v25, v25
	v_fmac_f32_e32 v237, v26, v26
	v_fmac_f32_e32 v237, v27, v27
	s_waitcnt vmcnt(32)
	v_fma_f32 v20, v20, 0.5, v196
	v_fma_f32 v21, v21, 0.5, v197
	v_fma_f32 v22, v22, 0.5, v198
	v_fma_f32 v23, v23, 0.5, v199
	v_fma_f32 v16, v16, 0.5, v200
	v_fma_f32 v17, v17, 0.5, v201
	v_fma_f32 v18, v18, 0.5, v202
	v_fma_f32 v19, v19, 0.5, v203
	global_store_dwordx4 v239, v[20:23], s[68:69] offset:512
	global_store_dwordx4 v239, v[16:19], s[68:69] offset:528
	v_cvt_pk_bf16_f32 v248, v20, v21
	v_cvt_pk_bf16_f32 v249, v22, v23
	v_cvt_pk_bf16_f32 v250, v16, v17
	v_cvt_pk_bf16_f32 v251, v18, v19
	global_store_dwordx4 v240, v[248:251], s[66:67] offset:256
	v_fmac_f32_e32 v237, v20, v20
	v_fmac_f32_e32 v237, v21, v21
	v_fmac_f32_e32 v237, v22, v22
	v_fmac_f32_e32 v237, v23, v23
	v_fmac_f32_e32 v237, v16, v16
	v_fmac_f32_e32 v237, v17, v17
	v_fmac_f32_e32 v237, v18, v18
	v_fmac_f32_e32 v237, v19, v19
	v_mov_b32_e32 v238, v237
	s_nop 1
	v_permlane16_swap_b32_e32 v237, v238
	v_add_f32_e32 v237, v237, v238
	v_mov_b32_e32 v238, v237
	s_nop 1
	v_permlane32_swap_b32_e32 v237, v238
	v_add_f32_e32 v237, v237, v238
	global_store_dword v241, v237, s[66:67]
	v_add_u32_e32 v239, 0xb0000, v234
	v_add_u32_e32 v240, 0x58000, v235
	v_add_u32_e32 v241, 0x2c00, v236
	s_waitcnt vmcnt(30)
	v_fma_f32 v12, v12, 0.5, v204
	v_fma_f32 v13, v13, 0.5, v205
	v_fma_f32 v14, v14, 0.5, v206
	v_fma_f32 v15, v15, 0.5, v207
	v_fma_f32 v8, v8, 0.5, v208
	v_fma_f32 v9, v9, 0.5, v209
	v_fma_f32 v10, v10, 0.5, v210
	v_fma_f32 v11, v11, 0.5, v211
	global_store_dwordx4 v239, v[12:15], s[68:69]
	global_store_dwordx4 v239, v[8:11], s[68:69] offset:16
	v_cvt_pk_bf16_f32 v244, v12, v13
	v_cvt_pk_bf16_f32 v245, v14, v15
	v_cvt_pk_bf16_f32 v246, v8, v9
	v_cvt_pk_bf16_f32 v247, v10, v11
	global_store_dwordx4 v240, v[244:247], s[66:67]
	v_mul_f32_e32 v237, v12, v12
	v_fmac_f32_e32 v237, v13, v13
	v_fmac_f32_e32 v237, v14, v14
	v_fmac_f32_e32 v237, v15, v15
	v_fmac_f32_e32 v237, v8, v8
	v_fmac_f32_e32 v237, v9, v9
	v_fmac_f32_e32 v237, v10, v10
	v_fmac_f32_e32 v237, v11, v11
	s_waitcnt vmcnt(28)
	v_fma_f32 v4, v4, 0.5, v212
	v_fma_f32 v5, v5, 0.5, v213
	v_fma_f32 v6, v6, 0.5, v214
	v_fma_f32 v7, v7, 0.5, v215
	v_fma_f32 v0, v0, 0.5, v216
	v_fma_f32 v1, v1, 0.5, v217
	v_fma_f32 v2, v2, 0.5, v218
	v_fma_f32 v3, v3, 0.5, v219
	global_store_dwordx4 v239, v[4:7], s[68:69] offset:512
	global_store_dwordx4 v239, v[0:3], s[68:69] offset:528
	v_cvt_pk_bf16_f32 v248, v4, v5
	v_cvt_pk_bf16_f32 v249, v6, v7
	v_cvt_pk_bf16_f32 v250, v0, v1
	v_cvt_pk_bf16_f32 v251, v2, v3
	global_store_dwordx4 v240, v[248:251], s[66:67] offset:256
	v_fmac_f32_e32 v237, v4, v4
	v_fmac_f32_e32 v237, v5, v5
	v_fmac_f32_e32 v237, v6, v6
	v_fmac_f32_e32 v237, v7, v7
	v_fmac_f32_e32 v237, v0, v0
	v_fmac_f32_e32 v237, v1, v1
	v_fmac_f32_e32 v237, v2, v2
	v_fmac_f32_e32 v237, v3, v3
	v_mov_b32_e32 v238, v237
	s_nop 1
	v_permlane16_swap_b32_e32 v237, v238
	v_add_f32_e32 v237, v237, v238
	v_mov_b32_e32 v238, v237
	s_nop 1
	v_permlane32_swap_b32_e32 v237, v238
	v_add_f32_e32 v237, v237, v238
	global_store_dword v241, v237, s[66:67]
	s_and_b64 vcc, exec, s[16:17]
	s_mov_b64 s[16:17], -1
	s_cbranch_vccnz .LBB0_2130
	s_andn2_b64 vcc, exec, s[22:23]
	s_cbranch_vccnz .LBB0_2129
	s_barrier
	s_branch .LBB0_2129

.LBB0_2379:
	s_mov_b64 s[0:1], s[66:67]
	s_mov_b64 s[8:9], s[68:69]
	v_mov_b32_e32 v6, v194
	v_and_b32_e32 v4, 63, v194
	v_lshrrev_b32_e32 v5, 6, v194
	v_and_b32_e32 v7, 1, v5
	v_lshl_or_b32 v4, v7, 8, v4
	v_lshrrev_b32_e32 v7, 1, v5
	s_and_b32 s16, s2, 1
	s_lshl_b32 s16, s16, 1
	v_add_u32_e32 v7, s16, v7
	v_lshl_or_b32 v4, v7, 6, v4
	s_lshr_b32 s16, s2, 1
	s_lshl_b32 s16, s16, 9
	v_or_b32_e32 v4, s16, v4
	v_mov_b32_e32 v7, 0x4000
	v_cmp_gt_u32_e32 vcc, 0x100, v194
	s_cmp_lt_u32 s2, 64
	s_cselect_b64 s[16:17], -1, 0
	s_nop 1
	s_and_b64 vcc, vcc, s[16:17]
	s_nop 1
	v_cndmask_b32_e32 v4, v7, v4, vcc
	v_mov_b32_e32 v5, 0
	s_mov_b64 s[14:15], 0x4000
	s_mov_b32 s8, s64
	v_cmp_gt_i64_e32 vcc, s[14:15], v[4:5]
	s_and_saveexec_b64 s[16:17], vcc
	s_cbranch_execz .LBB0_2468
	v_mov_b32_e32 v7, 0
	global_load_dwordx2 v[8:9], v7, s[0:1] offset:72
	global_load_dwordx4 v[0:3], v7, s[0:1] offset:56
	v_and_b32_e32 v10, 63, v6
	v_lshlrev_b32_e32 v6, 1, v6
	v_and_b32_e32 v11, 0x7e, v6
	v_lshlrev_b32_e32 v6, 2, v11
	s_ashr_i32 s9, s8, 31
	v_lshl_add_u64 v[12:13], s[0:1], 0, v[6:7]
	v_lshlrev_b32_e32 v6, 1, v11
	s_lshl_b64 s[18:19], s[8:9], 9
	s_mov_b64 s[8:9], 0xf000000
	v_lshl_add_u64 v[14:15], s[0:1], 0, v[6:7]
	s_mov_b64 s[0:1], 0xb800000
	v_lshl_add_u64 v[12:13], v[12:13], 0, s[8:9]
	v_lshl_add_u64 v[14:15], v[14:15], 0, s[0:1]
	s_mov_b64 s[20:21], 0
	s_mov_b32 s28, 0x3fb8aa3b
	s_mov_b32 s29, 0xc2ce8ed0
	s_mov_b32 s30, 0x42b17218
	v_mov_b32_e32 v11, 0x7f800000
	s_brev_b32 s31, 18
	s_mov_b32 s34, 0xfe5163ab
	s_mov_b32 s35, 0x3c439041
	s_mov_b32 s36, 0xdb629599
	s_mov_b32 s37, 0xf534ddc0
	s_mov_b32 s38, 0xfc2757d1
	s_mov_b32 s39, 0x4e441529
	s_mov_b32 s40, 0xa2f9836e
	s_mov_b32 s41, 0x3fc90fda
	s_mov_b32 s42, 0x3f22f983
	s_mov_b32 s43, 0xbfc90fda
	v_mov_b32_e32 v26, 0x3c0881c4
	v_mov_b32_e32 v27, 0xbab64f3b
	s_brev_b32 s44, 1
	s_movk_i32 s45, 0x1f8
	s_movk_i32 s48, 0x180
	s_movk_i32 s49, 0x7fff
	s_mov_b32 s51, 0xffff0000
	s_movk_i32 s52, 0x600
	s_mov_b64 s[22:23], 0x3fff
	v_not_b32_e32 v28, 63
	v_not_b32_e32 v29, 31
	v_mov_b32_e32 v30, 0x7fc00000

.LBB0_2468:
	s_or_b64 exec, exec, s[16:17]
	s_mov_b64 s[8:9], s[66:67]
	s_mov_b64 s[0:1], s[68:69]
	v_mov_b32_e32 v0, v194
	s_mov_b32 s40, s64
	s_abs_i32 s0, s40
	v_cvt_f32_u32_e32 v0, s0
	s_sub_i32 s15, 0, s0
	s_add_i32 s77, s77, s40
	s_abs_i32 s14, s77
	v_rcp_iflag_f32_e32 v0, v0
	s_ashr_i32 s1, s77, 31
	v_mov_b32_e32 v8, v194
	v_mul_f32_e32 v0, 0x4f7ffffe, v0
	v_cvt_u32_f32_e32 v0, v0
	v_readfirstlane_b32 s23, v8
	v_readfirstlane_b32 s16, v0
	s_mul_i32 s15, s15, s16
	s_mul_hi_u32 s15, s16, s15
	s_add_i32 s16, s16, s15
	s_mul_hi_u32 s15, s14, s16
	s_mul_i32 s15, s15, s0
	s_sub_i32 s14, s14, s15
	s_sub_i32 s15, s14, s0
	s_cmp_ge_u32 s14, s0
	s_cselect_b32 s14, s15, s14
	s_sub_i32 s15, s14, s0
	s_cmp_ge_u32 s14, s0
	s_cselect_b32 s0, s15, s14
	s_xor_b32 s0, s0, s1
	s_sub_i32 s41, s0, s1
	s_cmpk_gt_i32 s41, 0x7f
	s_cbranch_scc1 .LBB0_2403
	s_ashr_i32 s42, s41, 31
	s_lshr_b32 s0, s42, 29
	s_add_i32 s16, s41, s0
	s_and_b32 s0, s16, -8
	s_sub_i32 s15, s41, s0
	s_cmp_gt_i32 s15, -1
	s_cbranch_scc0 .LBB0_2382
	s_lshl_b32 s14, s15, 4
	s_ashr_i32 s0, s16, 3
	s_cbranch_execz .LBB0_2383
	s_branch .LBB0_2384

.LBB0_2403:
	s_getreg_b32 s8, hwreg(HW_REG_XCC_ID, 0, 4)
	s_waitcnt vmcnt(0)
	s_barrier
	s_and_saveexec_b64 s[0:1], s[46:47]
	s_cbranch_execz .LBB0_2520
	s_add_i32 s9, 0, 0x20160
	v_mov_b32_e32 v0, s9
	s_waitcnt vmcnt(0) expcnt(0) lgkmcnt(0)
	ds_read_b32 v2, v0
	s_add_i32 s9, 0, 0x20164
	v_mov_b32_e32 v0, s9
	ds_read_b32 v0, v0
	s_and_b32 s51, s8, 15
	s_waitcnt lgkmcnt(1)
	v_cmp_ne_u32_e32 vcc, 0, v2
	s_cbranch_vccnz .LBB0_2484
	s_add_u32 s8, s66, 0x1200
	s_addc_u32 s9, s67, 0
	s_add_u32 s14, s66, 0x1400
	s_addc_u32 s15, s67, 0
	s_add_u32 s16, s66, 0x1500
	s_addc_u32 s17, s67, 0
	s_add_u32 s18, s66, 0x1600
	s_addc_u32 s19, s67, 0
	s_add_u32 s20, s66, 0x1700
	s_addc_u32 s21, s67, 0
	s_add_u32 s22, s66, 0x1800
	s_addc_u32 s23, s67, 0
	s_add_u32 s24, s66, 0x1900
	s_addc_u32 s25, s67, 0
	s_add_u32 s26, s66, 0x1a00
	s_addc_u32 s27, s67, 0
	s_add_u32 s28, s66, 0x1b00
	s_addc_u32 s29, s67, 0
	s_add_u32 s30, s66, 0x1c00
	s_addc_u32 s31, s67, 0
	s_add_u32 s34, s66, 0x1d00
	s_addc_u32 s35, s67, 0
	s_add_u32 s36, s66, 0x1e00
	s_addc_u32 s37, s67, 0
	s_add_u32 s38, s66, 0x1f00
	s_addc_u32 s39, s67, 0
	s_add_u32 s40, s66, 0x2000
	s_addc_u32 s41, s67, 0
	s_add_u32 s42, s66, 0x2100
	s_addc_u32 s43, s67, 0
	s_add_u32 s44, s66, 0x2200
	s_addc_u32 s45, s67, 0
	s_mul_i32 s58, s65, s74
	s_add_u32 s48, s66, 0x2300
	s_mul_i32 s58, s58, s64
	s_addc_u32 s49, s67, 0
	s_mov_b32 s59, 1
	v_mov_b32_e32 v16, 0
	s_branch .LBB0_2472

.LBB0_3238:
	v_and_b32_e32 v252, 63, v194
	v_lshrrev_b32_e32 v253, 6, v194
	v_and_b32_e32 v254, 15, v252
	v_lshrrev_b32_e32 v255, 4, v252
	v_lshrrev_b32_e32 v252, 2, v253
	v_and_b32_e32 v253, 3, v253
	v_lshl_add_u32 v252, v252, 6, v254
	s_lshl_b32 s98, s34, 8
	v_add_u32_e32 v252, s98, v252
	v_lshlrev_b32_e32 v255, 3, v255
	v_lshl_add_u32 v255, v253, 5, v255
	s_lshl_b32 s98, s12, 8
	v_add_u32_e32 v255, s98, v255
	v_lshlrev_b32_e32 v234, 12, v252
	v_lshl_add_u32 v234, v255, 2, v234
	v_lshlrev_b32_e32 v235, 11, v252
	v_lshl_add_u32 v235, v255, 1, v235
	v_add_u32_e32 v235, 0x3800000, v235
	v_lshlrev_b32_e32 v236, 6, v252
	v_lshl_add_u32 v236, v253, 2, v236
	s_lshl_b32 s98, s12, 4
	s_add_i32 s98, s98, 0x3700000
	v_add_u32_e32 v236, s98, v236
	v_mov_b32_e32 v242, v234
	global_load_dwordx4 v[144:147], v242, s[68:69]
	global_load_dwordx4 v[156:159], v242, s[68:69] offset:16
	v_mov_b32_e32 v242, v234
	global_load_dwordx4 v[160:163], v242, s[68:69] offset:512
	global_load_dwordx4 v[164:167], v242, s[68:69] offset:528
	v_add_u32_e32 v242, 0x10000, v234
	global_load_dwordx4 v[168:171], v242, s[68:69]
	global_load_dwordx4 v[172:175], v242, s[68:69] offset:16
	v_add_u32_e32 v242, 0x10000, v234
	global_load_dwordx4 v[176:179], v242, s[68:69] offset:512
	global_load_dwordx4 v[180:183], v242, s[68:69] offset:528
	v_add_u32_e32 v242, 0x20000, v234
	global_load_dwordx4 v[184:187], v242, s[68:69]
	global_load_dwordx4 v[188:191], v242, s[68:69] offset:16
	v_add_u32_e32 v242, 0x20000, v234
	global_load_dwordx4 v[196:199], v242, s[68:69] offset:512
	global_load_dwordx4 v[200:203], v242, s[68:69] offset:528
	v_add_u32_e32 v242, 0x30000, v234
	global_load_dwordx4 v[204:207], v242, s[68:69]
	global_load_dwordx4 v[208:211], v242, s[68:69] offset:16
	v_add_u32_e32 v242, 0x30000, v234
	global_load_dwordx4 v[212:215], v242, s[68:69] offset:512
	global_load_dwordx4 v[216:219], v242, s[68:69] offset:528
	v_mov_b32_e32 v239, v234
	v_mov_b32_e32 v240, v235
	v_mov_b32_e32 v241, v236
	s_waitcnt vmcnt(14)
	v_add_f32_e32 v124, v124, v144
	v_add_f32_e32 v125, v125, v145
	v_add_f32_e32 v126, v126, v146
	v_add_f32_e32 v127, v127, v147
	v_add_f32_e32 v120, v120, v156
	v_add_f32_e32 v121, v121, v157
	v_add_f32_e32 v122, v122, v158
	v_add_f32_e32 v123, v123, v159
	v_add_u32_e32 v242, 0x80000, v234
	global_load_dwordx4 v[144:147], v242, s[68:69]
	global_load_dwordx4 v[156:159], v242, s[68:69] offset:16
	global_store_dwordx4 v239, v[124:127], s[68:69]
	global_store_dwordx4 v239, v[120:123], s[68:69] offset:16
	v_cvt_pk_bf16_f32 v244, v124, v125
	v_cvt_pk_bf16_f32 v245, v126, v127
	v_cvt_pk_bf16_f32 v246, v120, v121
	v_cvt_pk_bf16_f32 v247, v122, v123
	global_store_dwordx4 v240, v[244:247], s[66:67]
	v_mul_f32_e32 v237, v124, v124
	v_fmac_f32_e32 v237, v125, v125
	v_fmac_f32_e32 v237, v126, v126
	v_fmac_f32_e32 v237, v127, v127
	v_fmac_f32_e32 v237, v120, v120
	v_fmac_f32_e32 v237, v121, v121
	v_fmac_f32_e32 v237, v122, v122
	v_fmac_f32_e32 v237, v123, v123
	s_waitcnt vmcnt(17)
	v_add_f32_e32 v116, v116, v160
	v_add_f32_e32 v117, v117, v161
	v_add_f32_e32 v118, v118, v162
	v_add_f32_e32 v119, v119, v163
	v_add_f32_e32 v112, v112, v164
	v_add_f32_e32 v113, v113, v165
	v_add_f32_e32 v114, v114, v166
	v_add_f32_e32 v115, v115, v167
	v_add_u32_e32 v242, 0x80000, v234
	global_load_dwordx4 v[160:163], v242, s[68:69] offset:512
	global_load_dwordx4 v[164:167], v242, s[68:69] offset:528
	global_store_dwordx4 v239, v[116:119], s[68:69] offset:512
	global_store_dwordx4 v239, v[112:115], s[68:69] offset:528
	v_cvt_pk_bf16_f32 v248, v116, v117
	v_cvt_pk_bf16_f32 v249, v118, v119
	v_cvt_pk_bf16_f32 v250, v112, v113
	v_cvt_pk_bf16_f32 v251, v114, v115
	global_store_dwordx4 v240, v[248:251], s[66:67] offset:256
	v_fmac_f32_e32 v237, v116, v116
	v_fmac_f32_e32 v237, v117, v117
	v_fmac_f32_e32 v237, v118, v118
	v_fmac_f32_e32 v237, v119, v119
	v_fmac_f32_e32 v237, v112, v112
	v_fmac_f32_e32 v237, v113, v113
	v_fmac_f32_e32 v237, v114, v114
	v_fmac_f32_e32 v237, v115, v115
	v_mov_b32_e32 v238, v237
	s_nop 1
	v_permlane16_swap_b32_e32 v237, v238
	v_add_f32_e32 v237, v237, v238
	v_mov_b32_e32 v238, v237
	s_nop 1
	v_permlane32_swap_b32_e32 v237, v238
	v_add_f32_e32 v237, v237, v238
	global_store_dword v241, v237, s[66:67]
	v_add_u32_e32 v239, 0x10000, v234
	v_add_u32_e32 v240, 0x8000, v235
	v_add_u32_e32 v241, 0x400, v236
	s_waitcnt vmcnt(21)
	v_add_f32_e32 v108, v108, v168
	v_add_f32_e32 v109, v109, v169
	v_add_f32_e32 v110, v110, v170
	v_add_f32_e32 v111, v111, v171
	v_add_f32_e32 v104, v104, v172
	v_add_f32_e32 v105, v105, v173
	v_add_f32_e32 v106, v106, v174
	v_add_f32_e32 v107, v107, v175
	v_add_u32_e32 v242, 0x90000, v234
	global_load_dwordx4 v[168:171], v242, s[68:69]
	global_load_dwordx4 v[172:175], v242, s[68:69] offset:16
	global_store_dwordx4 v239, v[108:111], s[68:69]
	global_store_dwordx4 v239, v[104:107], s[68:69] offset:16
	v_cvt_pk_bf16_f32 v244, v108, v109
	v_cvt_pk_bf16_f32 v245, v110, v111
	v_cvt_pk_bf16_f32 v246, v104, v105
	v_cvt_pk_bf16_f32 v247, v106, v107
	global_store_dwordx4 v240, v[244:247], s[66:67]
	v_mul_f32_e32 v237, v108, v108
	v_fmac_f32_e32 v237, v109, v109
	v_fmac_f32_e32 v237, v110, v110
	v_fmac_f32_e32 v237, v111, v111
	v_fmac_f32_e32 v237, v104, v104
	v_fmac_f32_e32 v237, v105, v105
	v_fmac_f32_e32 v237, v106, v106
	v_fmac_f32_e32 v237, v107, v107
	s_waitcnt vmcnt(24)
	v_add_f32_e32 v100, v100, v176
	v_add_f32_e32 v101, v101, v177
	v_add_f32_e32 v102, v102, v178
	v_add_f32_e32 v103, v103, v179
	v_add_f32_e32 v96, v96, v180
	v_add_f32_e32 v97, v97, v181
	v_add_f32_e32 v98, v98, v182
	v_add_f32_e32 v99, v99, v183
	v_add_u32_e32 v242, 0x90000, v234
	global_load_dwordx4 v[176:179], v242, s[68:69] offset:512
	global_load_dwordx4 v[180:183], v242, s[68:69] offset:528
	global_store_dwordx4 v239, v[100:103], s[68:69] offset:512
	global_store_dwordx4 v239, v[96:99], s[68:69] offset:528
	v_cvt_pk_bf16_f32 v248, v100, v101
	v_cvt_pk_bf16_f32 v249, v102, v103
	v_cvt_pk_bf16_f32 v250, v96, v97
	v_cvt_pk_bf16_f32 v251, v98, v99
	global_store_dwordx4 v240, v[248:251], s[66:67] offset:256
	v_fmac_f32_e32 v237, v100, v100
	v_fmac_f32_e32 v237, v101, v101
	v_fmac_f32_e32 v237, v102, v102
	v_fmac_f32_e32 v237, v103, v103
	v_fmac_f32_e32 v237, v96, v96
	v_fmac_f32_e32 v237, v97, v97
	v_fmac_f32_e32 v237, v98, v98
	v_fmac_f32_e32 v237, v99, v99
	v_mov_b32_e32 v238, v237
	s_nop 1
	v_permlane16_swap_b32_e32 v237, v238
	v_add_f32_e32 v237, v237, v238
	v_mov_b32_e32 v238, v237
	s_nop 1
	v_permlane32_swap_b32_e32 v237, v238
	v_add_f32_e32 v237, v237, v238
	global_store_dword v241, v237, s[66:67]
	v_add_u32_e32 v239, 0x20000, v234
	v_add_u32_e32 v240, 0x10000, v235
	v_add_u32_e32 v241, 0x800, v236
	s_waitcnt vmcnt(28)
	v_add_f32_e32 v92, v92, v184
	v_add_f32_e32 v93, v93, v185
	v_add_f32_e32 v94, v94, v186
	v_add_f32_e32 v95, v95, v187
	v_add_f32_e32 v88, v88, v188
	v_add_f32_e32 v89, v89, v189
	v_add_f32_e32 v90, v90, v190
	v_add_f32_e32 v91, v91, v191
	v_add_u32_e32 v242, 0xa0000, v234
	global_load_dwordx4 v[184:187], v242, s[68:69]
	global_load_dwordx4 v[188:191], v242, s[68:69] offset:16
	global_store_dwordx4 v239, v[92:95], s[68:69]
	global_store_dwordx4 v239, v[88:91], s[68:69] offset:16
	v_cvt_pk_bf16_f32 v244, v92, v93
	v_cvt_pk_bf16_f32 v245, v94, v95
	v_cvt_pk_bf16_f32 v246, v88, v89
	v_cvt_pk_bf16_f32 v247, v90, v91
	global_store_dwordx4 v240, v[244:247], s[66:67]
	v_mul_f32_e32 v237, v92, v92
	v_fmac_f32_e32 v237, v93, v93
	v_fmac_f32_e32 v237, v94, v94
	v_fmac_f32_e32 v237, v95, v95
	v_fmac_f32_e32 v237, v88, v88
	v_fmac_f32_e32 v237, v89, v89
	v_fmac_f32_e32 v237, v90, v90
	v_fmac_f32_e32 v237, v91, v91
	s_waitcnt vmcnt(31)
	v_add_f32_e32 v84, v84, v196
	v_add_f32_e32 v85, v85, v197
	v_add_f32_e32 v86, v86, v198
	v_add_f32_e32 v87, v87, v199
	v_add_f32_e32 v80, v80, v200
	v_add_f32_e32 v81, v81, v201
	v_add_f32_e32 v82, v82, v202
	v_add_f32_e32 v83, v83, v203
	v_add_u32_e32 v242, 0xa0000, v234
	global_load_dwordx4 v[196:199], v242, s[68:69] offset:512
	global_load_dwordx4 v[200:203], v242, s[68:69] offset:528
	global_store_dwordx4 v239, v[84:87], s[68:69] offset:512
	global_store_dwordx4 v239, v[80:83], s[68:69] offset:528
	v_cvt_pk_bf16_f32 v248, v84, v85
	v_cvt_pk_bf16_f32 v249, v86, v87
	v_cvt_pk_bf16_f32 v250, v80, v81
	v_cvt_pk_bf16_f32 v251, v82, v83
	global_store_dwordx4 v240, v[248:251], s[66:67] offset:256
	v_fmac_f32_e32 v237, v84, v84
	v_fmac_f32_e32 v237, v85, v85
	v_fmac_f32_e32 v237, v86, v86
	v_fmac_f32_e32 v237, v87, v87
	v_fmac_f32_e32 v237, v80, v80
	v_fmac_f32_e32 v237, v81, v81
	v_fmac_f32_e32 v237, v82, v82
	v_fmac_f32_e32 v237, v83, v83
	v_mov_b32_e32 v238, v237
	s_nop 1
	v_permlane16_swap_b32_e32 v237, v238
	v_add_f32_e32 v237, v237, v238
	v_mov_b32_e32 v238, v237
	s_nop 1
	v_permlane32_swap_b32_e32 v237, v238
	v_add_f32_e32 v237, v237, v238
	global_store_dword v241, v237, s[66:67]
	v_add_u32_e32 v239, 0x30000, v234
	v_add_u32_e32 v240, 0x18000, v235
	v_add_u32_e32 v241, 0xc00, v236
	s_waitcnt vmcnt(35)
	v_add_f32_e32 v76, v76, v204
	v_add_f32_e32 v77, v77, v205
	v_add_f32_e32 v78, v78, v206
	v_add_f32_e32 v79, v79, v207
	v_add_f32_e32 v72, v72, v208
	v_add_f32_e32 v73, v73, v209
	v_add_f32_e32 v74, v74, v210
	v_add_f32_e32 v75, v75, v211
	v_add_u32_e32 v242, 0xb0000, v234
	global_load_dwordx4 v[204:207], v242, s[68:69]
	global_load_dwordx4 v[208:211], v242, s[68:69] offset:16
	global_store_dwordx4 v239, v[76:79], s[68:69]
	global_store_dwordx4 v239, v[72:75], s[68:69] offset:16
	v_cvt_pk_bf16_f32 v244, v76, v77
	v_cvt_pk_bf16_f32 v245, v78, v79
	v_cvt_pk_bf16_f32 v246, v72, v73
	v_cvt_pk_bf16_f32 v247, v74, v75
	global_store_dwordx4 v240, v[244:247], s[66:67]
	v_mul_f32_e32 v237, v76, v76
	v_fmac_f32_e32 v237, v77, v77
	v_fmac_f32_e32 v237, v78, v78
	v_fmac_f32_e32 v237, v79, v79
	v_fmac_f32_e32 v237, v72, v72
	v_fmac_f32_e32 v237, v73, v73
	v_fmac_f32_e32 v237, v74, v74
	v_fmac_f32_e32 v237, v75, v75
	s_waitcnt vmcnt(38)
	v_add_f32_e32 v68, v68, v212
	v_add_f32_e32 v69, v69, v213
	v_add_f32_e32 v70, v70, v214
	v_add_f32_e32 v71, v71, v215
	v_add_f32_e32 v64, v64, v216
	v_add_f32_e32 v65, v65, v217
	v_add_f32_e32 v66, v66, v218
	v_add_f32_e32 v67, v67, v219
	v_add_u32_e32 v242, 0xb0000, v234
	global_load_dwordx4 v[212:215], v242, s[68:69] offset:512
	global_load_dwordx4 v[216:219], v242, s[68:69] offset:528
	global_store_dwordx4 v239, v[68:71], s[68:69] offset:512
	global_store_dwordx4 v239, v[64:67], s[68:69] offset:528
	v_cvt_pk_bf16_f32 v248, v68, v69
	v_cvt_pk_bf16_f32 v249, v70, v71
	v_cvt_pk_bf16_f32 v250, v64, v65
	v_cvt_pk_bf16_f32 v251, v66, v67
	global_store_dwordx4 v240, v[248:251], s[66:67] offset:256
	v_fmac_f32_e32 v237, v68, v68
	v_fmac_f32_e32 v237, v69, v69
	v_fmac_f32_e32 v237, v70, v70
	v_fmac_f32_e32 v237, v71, v71
	v_fmac_f32_e32 v237, v64, v64
	v_fmac_f32_e32 v237, v65, v65
	v_fmac_f32_e32 v237, v66, v66
	v_fmac_f32_e32 v237, v67, v67
	v_mov_b32_e32 v238, v237
	s_nop 1
	v_permlane16_swap_b32_e32 v237, v238
	v_add_f32_e32 v237, v237, v238
	v_mov_b32_e32 v238, v237
	s_nop 1
	v_permlane32_swap_b32_e32 v237, v238
	v_add_f32_e32 v237, v237, v238
	global_store_dword v241, v237, s[66:67]
	v_add_u32_e32 v239, 0x80000, v234
	v_add_u32_e32 v240, 0x40000, v235
	v_add_u32_e32 v241, 0x2000, v236
	s_waitcnt vmcnt(42)
	v_add_f32_e32 v60, v60, v144
	v_add_f32_e32 v61, v61, v145
	v_add_f32_e32 v62, v62, v146
	v_add_f32_e32 v63, v63, v147
	v_add_f32_e32 v56, v56, v156
	v_add_f32_e32 v57, v57, v157
	v_add_f32_e32 v58, v58, v158
	v_add_f32_e32 v59, v59, v159
	global_store_dwordx4 v239, v[60:63], s[68:69]
	global_store_dwordx4 v239, v[56:59], s[68:69] offset:16
	v_cvt_pk_bf16_f32 v244, v60, v61
	v_cvt_pk_bf16_f32 v245, v62, v63
	v_cvt_pk_bf16_f32 v246, v56, v57
	v_cvt_pk_bf16_f32 v247, v58, v59
	global_store_dwordx4 v240, v[244:247], s[66:67]
	v_mul_f32_e32 v237, v60, v60
	v_fmac_f32_e32 v237, v61, v61
	v_fmac_f32_e32 v237, v62, v62
	v_fmac_f32_e32 v237, v63, v63
	v_fmac_f32_e32 v237, v56, v56
	v_fmac_f32_e32 v237, v57, v57
	v_fmac_f32_e32 v237, v58, v58
	v_fmac_f32_e32 v237, v59, v59
	s_waitcnt vmcnt(40)
	v_add_f32_e32 v52, v52, v160
	v_add_f32_e32 v53, v53, v161
	v_add_f32_e32 v54, v54, v162
	v_add_f32_e32 v55, v55, v163
	v_add_f32_e32 v48, v48, v164
	v_add_f32_e32 v49, v49, v165
	v_add_f32_e32 v50, v50, v166
	v_add_f32_e32 v51, v51, v167
	global_store_dwordx4 v239, v[52:55], s[68:69] offset:512
	global_store_dwordx4 v239, v[48:51], s[68:69] offset:528
	v_cvt_pk_bf16_f32 v248, v52, v53
	v_cvt_pk_bf16_f32 v249, v54, v55
	v_cvt_pk_bf16_f32 v250, v48, v49
	v_cvt_pk_bf16_f32 v251, v50, v51
	global_store_dwordx4 v240, v[248:251], s[66:67] offset:256
	v_fmac_f32_e32 v237, v52, v52
	v_fmac_f32_e32 v237, v53, v53
	v_fmac_f32_e32 v237, v54, v54
	v_fmac_f32_e32 v237, v55, v55
	v_fmac_f32_e32 v237, v48, v48
	v_fmac_f32_e32 v237, v49, v49
	v_fmac_f32_e32 v237, v50, v50
	v_fmac_f32_e32 v237, v51, v51
	v_mov_b32_e32 v238, v237
	s_nop 1
	v_permlane16_swap_b32_e32 v237, v238
	v_add_f32_e32 v237, v237, v238
	v_mov_b32_e32 v238, v237
	s_nop 1
	v_permlane32_swap_b32_e32 v237, v238
	v_add_f32_e32 v237, v237, v238
	global_store_dword v241, v237, s[66:67]
	v_add_u32_e32 v239, 0x90000, v234
	v_add_u32_e32 v240, 0x48000, v235
	v_add_u32_e32 v241, 0x2400, v236
	s_waitcnt vmcnt(38)
	v_add_f32_e32 v44, v44, v168
	v_add_f32_e32 v45, v45, v169
	v_add_f32_e32 v46, v46, v170
	v_add_f32_e32 v47, v47, v171
	v_add_f32_e32 v40, v40, v172
	v_add_f32_e32 v41, v41, v173
	v_add_f32_e32 v42, v42, v174
	v_add_f32_e32 v43, v43, v175
	global_store_dwordx4 v239, v[44:47], s[68:69]
	global_store_dwordx4 v239, v[40:43], s[68:69] offset:16
	v_cvt_pk_bf16_f32 v244, v44, v45
	v_cvt_pk_bf16_f32 v245, v46, v47
	v_cvt_pk_bf16_f32 v246, v40, v41
	v_cvt_pk_bf16_f32 v247, v42, v43
	global_store_dwordx4 v240, v[244:247], s[66:67]
	v_mul_f32_e32 v237, v44, v44
	v_fmac_f32_e32 v237, v45, v45
	v_fmac_f32_e32 v237, v46, v46
	v_fmac_f32_e32 v237, v47, v47
	v_fmac_f32_e32 v237, v40, v40
	v_fmac_f32_e32 v237, v41, v41
	v_fmac_f32_e32 v237, v42, v42
	v_fmac_f32_e32 v237, v43, v43
	s_waitcnt vmcnt(36)
	v_add_f32_e32 v36, v36, v176
	v_add_f32_e32 v37, v37, v177
	v_add_f32_e32 v38, v38, v178
	v_add_f32_e32 v39, v39, v179
	v_add_f32_e32 v32, v32, v180
	v_add_f32_e32 v33, v33, v181
	v_add_f32_e32 v34, v34, v182
	v_add_f32_e32 v35, v35, v183
	global_store_dwordx4 v239, v[36:39], s[68:69] offset:512
	global_store_dwordx4 v239, v[32:35], s[68:69] offset:528
	v_cvt_pk_bf16_f32 v248, v36, v37
	v_cvt_pk_bf16_f32 v249, v38, v39
	v_cvt_pk_bf16_f32 v250, v32, v33
	v_cvt_pk_bf16_f32 v251, v34, v35
	global_store_dwordx4 v240, v[248:251], s[66:67] offset:256
	v_fmac_f32_e32 v237, v36, v36
	v_fmac_f32_e32 v237, v37, v37
	v_fmac_f32_e32 v237, v38, v38
	v_fmac_f32_e32 v237, v39, v39
	v_fmac_f32_e32 v237, v32, v32
	v_fmac_f32_e32 v237, v33, v33
	v_fmac_f32_e32 v237, v34, v34
	v_fmac_f32_e32 v237, v35, v35
	v_mov_b32_e32 v238, v237
	s_nop 1
	v_permlane16_swap_b32_e32 v237, v238
	v_add_f32_e32 v237, v237, v238
	v_mov_b32_e32 v238, v237
	s_nop 1
	v_permlane32_swap_b32_e32 v237, v238
	v_add_f32_e32 v237, v237, v238
	global_store_dword v241, v237, s[66:67]
	v_add_u32_e32 v239, 0xa0000, v234
	v_add_u32_e32 v240, 0x50000, v235
	v_add_u32_e32 v241, 0x2800, v236
	s_waitcnt vmcnt(34)
	v_add_f32_e32 v28, v28, v184
	v_add_f32_e32 v29, v29, v185
	v_add_f32_e32 v30, v30, v186
	v_add_f32_e32 v31, v31, v187
	v_add_f32_e32 v24, v24, v188
	v_add_f32_e32 v25, v25, v189
	v_add_f32_e32 v26, v26, v190
	v_add_f32_e32 v27, v27, v191
	global_store_dwordx4 v239, v[28:31], s[68:69]
	global_store_dwordx4 v239, v[24:27], s[68:69] offset:16
	v_cvt_pk_bf16_f32 v244, v28, v29
	v_cvt_pk_bf16_f32 v245, v30, v31
	v_cvt_pk_bf16_f32 v246, v24, v25
	v_cvt_pk_bf16_f32 v247, v26, v27
	global_store_dwordx4 v240, v[244:247], s[66:67]
	v_mul_f32_e32 v237, v28, v28
	v_fmac_f32_e32 v237, v29, v29
	v_fmac_f32_e32 v237, v30, v30
	v_fmac_f32_e32 v237, v31, v31
	v_fmac_f32_e32 v237, v24, v24
	v_fmac_f32_e32 v237, v25, v25
	v_fmac_f32_e32 v237, v26, v26
	v_fmac_f32_e32 v237, v27, v27
	s_waitcnt vmcnt(32)
	v_add_f32_e32 v20, v20, v196
	v_add_f32_e32 v21, v21, v197
	v_add_f32_e32 v22, v22, v198
	v_add_f32_e32 v23, v23, v199
	v_add_f32_e32 v16, v16, v200
	v_add_f32_e32 v17, v17, v201
	v_add_f32_e32 v18, v18, v202
	v_add_f32_e32 v19, v19, v203
	global_store_dwordx4 v239, v[20:23], s[68:69] offset:512
	global_store_dwordx4 v239, v[16:19], s[68:69] offset:528
	v_cvt_pk_bf16_f32 v248, v20, v21
	v_cvt_pk_bf16_f32 v249, v22, v23
	v_cvt_pk_bf16_f32 v250, v16, v17
	v_cvt_pk_bf16_f32 v251, v18, v19
	global_store_dwordx4 v240, v[248:251], s[66:67] offset:256
	v_fmac_f32_e32 v237, v20, v20
	v_fmac_f32_e32 v237, v21, v21
	v_fmac_f32_e32 v237, v22, v22
	v_fmac_f32_e32 v237, v23, v23
	v_fmac_f32_e32 v237, v16, v16
	v_fmac_f32_e32 v237, v17, v17
	v_fmac_f32_e32 v237, v18, v18
	v_fmac_f32_e32 v237, v19, v19
	v_mov_b32_e32 v238, v237
	s_nop 1
	v_permlane16_swap_b32_e32 v237, v238
	v_add_f32_e32 v237, v237, v238
	v_mov_b32_e32 v238, v237
	s_nop 1
	v_permlane32_swap_b32_e32 v237, v238
	v_add_f32_e32 v237, v237, v238
	global_store_dword v241, v237, s[66:67]
	v_add_u32_e32 v239, 0xb0000, v234
	v_add_u32_e32 v240, 0x58000, v235
	v_add_u32_e32 v241, 0x2c00, v236
	s_waitcnt vmcnt(30)
	v_add_f32_e32 v12, v12, v204
	v_add_f32_e32 v13, v13, v205
	v_add_f32_e32 v14, v14, v206
	v_add_f32_e32 v15, v15, v207
	v_add_f32_e32 v8, v8, v208
	v_add_f32_e32 v9, v9, v209
	v_add_f32_e32 v10, v10, v210
	v_add_f32_e32 v11, v11, v211
	global_store_dwordx4 v239, v[12:15], s[68:69]
	global_store_dwordx4 v239, v[8:11], s[68:69] offset:16
	v_cvt_pk_bf16_f32 v244, v12, v13
	v_cvt_pk_bf16_f32 v245, v14, v15
	v_cvt_pk_bf16_f32 v246, v8, v9
	v_cvt_pk_bf16_f32 v247, v10, v11
	global_store_dwordx4 v240, v[244:247], s[66:67]
	v_mul_f32_e32 v237, v12, v12
	v_fmac_f32_e32 v237, v13, v13
	v_fmac_f32_e32 v237, v14, v14
	v_fmac_f32_e32 v237, v15, v15
	v_fmac_f32_e32 v237, v8, v8
	v_fmac_f32_e32 v237, v9, v9
	v_fmac_f32_e32 v237, v10, v10
	v_fmac_f32_e32 v237, v11, v11
	s_waitcnt vmcnt(28)
	v_add_f32_e32 v4, v4, v212
	v_add_f32_e32 v5, v5, v213
	v_add_f32_e32 v6, v6, v214
	v_add_f32_e32 v7, v7, v215
	v_add_f32_e32 v0, v0, v216
	v_add_f32_e32 v1, v1, v217
	v_add_f32_e32 v2, v2, v218
	v_add_f32_e32 v3, v3, v219
	global_store_dwordx4 v239, v[4:7], s[68:69] offset:512
	global_store_dwordx4 v239, v[0:3], s[68:69] offset:528
	v_cvt_pk_bf16_f32 v248, v4, v5
	v_cvt_pk_bf16_f32 v249, v6, v7
	v_cvt_pk_bf16_f32 v250, v0, v1
	v_cvt_pk_bf16_f32 v251, v2, v3
	global_store_dwordx4 v240, v[248:251], s[66:67] offset:256
	v_fmac_f32_e32 v237, v4, v4
	v_fmac_f32_e32 v237, v5, v5
	v_fmac_f32_e32 v237, v6, v6
	v_fmac_f32_e32 v237, v7, v7
	v_fmac_f32_e32 v237, v0, v0
	v_fmac_f32_e32 v237, v1, v1
	v_fmac_f32_e32 v237, v2, v2
	v_fmac_f32_e32 v237, v3, v3
	v_mov_b32_e32 v238, v237
	s_nop 1
	v_permlane16_swap_b32_e32 v237, v238
	v_add_f32_e32 v237, v237, v238
	v_mov_b32_e32 v238, v237
	s_nop 1
	v_permlane32_swap_b32_e32 v237, v238
	v_add_f32_e32 v237, v237, v238
	global_store_dword v241, v237, s[66:67]
	s_andn2_b64 vcc, exec, s[10:11]
	s_mov_b64 s[10:11], -1
	s_cbranch_vccnz .LBB0_3227
	s_andn2_b64 vcc, exec, s[14:15]
	s_cbranch_vccnz .LBB0_3226
	s_barrier
	s_branch .LBB0_3226

.LBB0_3404:
	v_and_b32_e32 v252, 63, v194
	v_lshrrev_b32_e32 v253, 6, v194
	v_and_b32_e32 v254, 15, v252
	v_lshrrev_b32_e32 v255, 4, v252
	v_lshrrev_b32_e32 v252, 2, v253
	v_and_b32_e32 v253, 3, v253
	v_lshl_add_u32 v252, v252, 6, v254
	s_lshl_b32 s98, s53, 8
	v_add_u32_e32 v252, s98, v252
	v_lshlrev_b32_e32 v255, 3, v255
	v_lshl_add_u32 v255, v253, 5, v255
	s_lshl_b32 s98, s10, 8
	v_add_u32_e32 v255, s98, v255
	v_lshlrev_b32_e32 v234, 12, v252
	v_lshl_add_u32 v234, v255, 2, v234
	v_lshlrev_b32_e32 v235, 11, v252
	v_lshl_add_u32 v235, v255, 1, v235
	v_add_u32_e32 v235, 0x3800000, v235
	v_lshlrev_b32_e32 v236, 6, v252
	v_lshl_add_u32 v236, v253, 2, v236
	s_lshl_b32 s98, s10, 4
	s_add_i32 s98, s98, 0x3500000
	v_add_u32_e32 v236, s98, v236
	v_mov_b32_e32 v242, v234
	global_load_dwordx4 v[144:147], v242, s[68:69]
	global_load_dwordx4 v[156:159], v242, s[68:69] offset:16
	v_mov_b32_e32 v242, v234
	global_load_dwordx4 v[160:163], v242, s[68:69] offset:512
	global_load_dwordx4 v[164:167], v242, s[68:69] offset:528
	v_add_u32_e32 v242, 0x10000, v234
	global_load_dwordx4 v[168:171], v242, s[68:69]
	global_load_dwordx4 v[172:175], v242, s[68:69] offset:16
	v_add_u32_e32 v242, 0x10000, v234
	global_load_dwordx4 v[176:179], v242, s[68:69] offset:512
	global_load_dwordx4 v[180:183], v242, s[68:69] offset:528
	v_add_u32_e32 v242, 0x20000, v234
	global_load_dwordx4 v[184:187], v242, s[68:69]
	global_load_dwordx4 v[188:191], v242, s[68:69] offset:16
	v_add_u32_e32 v242, 0x20000, v234
	global_load_dwordx4 v[196:199], v242, s[68:69] offset:512
	global_load_dwordx4 v[200:203], v242, s[68:69] offset:528
	v_add_u32_e32 v242, 0x30000, v234
	global_load_dwordx4 v[204:207], v242, s[68:69]
	global_load_dwordx4 v[208:211], v242, s[68:69] offset:16
	v_add_u32_e32 v242, 0x30000, v234
	global_load_dwordx4 v[212:215], v242, s[68:69] offset:512
	global_load_dwordx4 v[216:219], v242, s[68:69] offset:528
	v_mov_b32_e32 v239, v234
	v_mov_b32_e32 v241, v236
	s_waitcnt vmcnt(14)
	v_fma_f32 v124, v124, 0.5, v144
	v_fma_f32 v125, v125, 0.5, v145
	v_fma_f32 v126, v126, 0.5, v146
	v_fma_f32 v127, v127, 0.5, v147
	v_fma_f32 v120, v120, 0.5, v156
	v_fma_f32 v121, v121, 0.5, v157
	v_fma_f32 v122, v122, 0.5, v158
	v_fma_f32 v123, v123, 0.5, v159
	v_add_u32_e32 v242, 0x80000, v234
	global_load_dwordx4 v[144:147], v242, s[68:69]
	global_load_dwordx4 v[156:159], v242, s[68:69] offset:16
	global_store_dwordx4 v239, v[124:127], s[68:69]
	global_store_dwordx4 v239, v[120:123], s[68:69] offset:16
	v_mul_f32_e32 v237, v124, v124
	v_fmac_f32_e32 v237, v125, v125
	v_fmac_f32_e32 v237, v126, v126
	v_fmac_f32_e32 v237, v127, v127
	v_fmac_f32_e32 v237, v120, v120
	v_fmac_f32_e32 v237, v121, v121
	v_fmac_f32_e32 v237, v122, v122
	v_fmac_f32_e32 v237, v123, v123
	s_waitcnt vmcnt(16)
	v_fma_f32 v116, v116, 0.5, v160
	v_fma_f32 v117, v117, 0.5, v161
	v_fma_f32 v118, v118, 0.5, v162
	v_fma_f32 v119, v119, 0.5, v163
	v_fma_f32 v112, v112, 0.5, v164
	v_fma_f32 v113, v113, 0.5, v165
	v_fma_f32 v114, v114, 0.5, v166
	v_fma_f32 v115, v115, 0.5, v167
	v_add_u32_e32 v242, 0x80000, v234
	global_load_dwordx4 v[160:163], v242, s[68:69] offset:512
	global_load_dwordx4 v[164:167], v242, s[68:69] offset:528
	global_store_dwordx4 v239, v[116:119], s[68:69] offset:512
	global_store_dwordx4 v239, v[112:115], s[68:69] offset:528
	v_fmac_f32_e32 v237, v116, v116
	v_fmac_f32_e32 v237, v117, v117
	v_fmac_f32_e32 v237, v118, v118
	v_fmac_f32_e32 v237, v119, v119
	v_fmac_f32_e32 v237, v112, v112
	v_fmac_f32_e32 v237, v113, v113
	v_fmac_f32_e32 v237, v114, v114
	v_fmac_f32_e32 v237, v115, v115
	v_mov_b32_e32 v238, v237
	s_nop 1
	v_permlane16_swap_b32_e32 v237, v238
	v_add_f32_e32 v237, v237, v238
	v_mov_b32_e32 v238, v237
	s_nop 1
	v_permlane32_swap_b32_e32 v237, v238
	v_add_f32_e32 v237, v237, v238
	global_store_dword v241, v237, s[66:67]
	v_add_u32_e32 v239, 0x10000, v234
	v_add_u32_e32 v241, 0x400, v236
	s_waitcnt vmcnt(19)
	v_fma_f32 v108, v108, 0.5, v168
	v_fma_f32 v109, v109, 0.5, v169
	v_fma_f32 v110, v110, 0.5, v170
	v_fma_f32 v111, v111, 0.5, v171
	v_fma_f32 v104, v104, 0.5, v172
	v_fma_f32 v105, v105, 0.5, v173
	v_fma_f32 v106, v106, 0.5, v174
	v_fma_f32 v107, v107, 0.5, v175
	v_add_u32_e32 v242, 0x90000, v234
	global_load_dwordx4 v[168:171], v242, s[68:69]
	global_load_dwordx4 v[172:175], v242, s[68:69] offset:16
	global_store_dwordx4 v239, v[108:111], s[68:69]
	global_store_dwordx4 v239, v[104:107], s[68:69] offset:16
	v_mul_f32_e32 v237, v108, v108
	v_fmac_f32_e32 v237, v109, v109
	v_fmac_f32_e32 v237, v110, v110
	v_fmac_f32_e32 v237, v111, v111
	v_fmac_f32_e32 v237, v104, v104
	v_fmac_f32_e32 v237, v105, v105
	v_fmac_f32_e32 v237, v106, v106
	v_fmac_f32_e32 v237, v107, v107
	s_waitcnt vmcnt(21)
	v_fma_f32 v100, v100, 0.5, v176
	v_fma_f32 v101, v101, 0.5, v177
	v_fma_f32 v102, v102, 0.5, v178
	v_fma_f32 v103, v103, 0.5, v179
	v_fma_f32 v96, v96, 0.5, v180
	v_fma_f32 v97, v97, 0.5, v181
	v_fma_f32 v98, v98, 0.5, v182
	v_fma_f32 v99, v99, 0.5, v183
	v_add_u32_e32 v242, 0x90000, v234
	global_load_dwordx4 v[176:179], v242, s[68:69] offset:512
	global_load_dwordx4 v[180:183], v242, s[68:69] offset:528
	global_store_dwordx4 v239, v[100:103], s[68:69] offset:512
	global_store_dwordx4 v239, v[96:99], s[68:69] offset:528
	v_fmac_f32_e32 v237, v100, v100
	v_fmac_f32_e32 v237, v101, v101
	v_fmac_f32_e32 v237, v102, v102
	v_fmac_f32_e32 v237, v103, v103
	v_fmac_f32_e32 v237, v96, v96
	v_fmac_f32_e32 v237, v97, v97
	v_fmac_f32_e32 v237, v98, v98
	v_fmac_f32_e32 v237, v99, v99
	v_mov_b32_e32 v238, v237
	s_nop 1
	v_permlane16_swap_b32_e32 v237, v238
	v_add_f32_e32 v237, v237, v238
	v_mov_b32_e32 v238, v237
	s_nop 1
	v_permlane32_swap_b32_e32 v237, v238
	v_add_f32_e32 v237, v237, v238
	global_store_dword v241, v237, s[66:67]
	v_add_u32_e32 v239, 0x20000, v234
	v_add_u32_e32 v241, 0x800, v236
	s_waitcnt vmcnt(24)
	v_fma_f32 v92, v92, 0.5, v184
	v_fma_f32 v93, v93, 0.5, v185
	v_fma_f32 v94, v94, 0.5, v186
	v_fma_f32 v95, v95, 0.5, v187
	v_fma_f32 v88, v88, 0.5, v188
	v_fma_f32 v89, v89, 0.5, v189
	v_fma_f32 v90, v90, 0.5, v190
	v_fma_f32 v91, v91, 0.5, v191
	v_add_u32_e32 v242, 0xa0000, v234
	global_load_dwordx4 v[184:187], v242, s[68:69]
	global_load_dwordx4 v[188:191], v242, s[68:69] offset:16
	global_store_dwordx4 v239, v[92:95], s[68:69]
	global_store_dwordx4 v239, v[88:91], s[68:69] offset:16
	v_mul_f32_e32 v237, v92, v92
	v_fmac_f32_e32 v237, v93, v93
	v_fmac_f32_e32 v237, v94, v94
	v_fmac_f32_e32 v237, v95, v95
	v_fmac_f32_e32 v237, v88, v88
	v_fmac_f32_e32 v237, v89, v89
	v_fmac_f32_e32 v237, v90, v90
	v_fmac_f32_e32 v237, v91, v91
	s_waitcnt vmcnt(26)
	v_fma_f32 v84, v84, 0.5, v196
	v_fma_f32 v85, v85, 0.5, v197
	v_fma_f32 v86, v86, 0.5, v198
	v_fma_f32 v87, v87, 0.5, v199
	v_fma_f32 v80, v80, 0.5, v200
	v_fma_f32 v81, v81, 0.5, v201
	v_fma_f32 v82, v82, 0.5, v202
	v_fma_f32 v83, v83, 0.5, v203
	v_add_u32_e32 v242, 0xa0000, v234
	global_load_dwordx4 v[196:199], v242, s[68:69] offset:512
	global_load_dwordx4 v[200:203], v242, s[68:69] offset:528
	global_store_dwordx4 v239, v[84:87], s[68:69] offset:512
	global_store_dwordx4 v239, v[80:83], s[68:69] offset:528
	v_fmac_f32_e32 v237, v84, v84
	v_fmac_f32_e32 v237, v85, v85
	v_fmac_f32_e32 v237, v86, v86
	v_fmac_f32_e32 v237, v87, v87
	v_fmac_f32_e32 v237, v80, v80
	v_fmac_f32_e32 v237, v81, v81
	v_fmac_f32_e32 v237, v82, v82
	v_fmac_f32_e32 v237, v83, v83
	v_mov_b32_e32 v238, v237
	s_nop 1
	v_permlane16_swap_b32_e32 v237, v238
	v_add_f32_e32 v237, v237, v238
	v_mov_b32_e32 v238, v237
	s_nop 1
	v_permlane32_swap_b32_e32 v237, v238
	v_add_f32_e32 v237, v237, v238
	global_store_dword v241, v237, s[66:67]
	v_add_u32_e32 v239, 0x30000, v234
	v_add_u32_e32 v241, 0xc00, v236
	s_waitcnt vmcnt(29)
	v_fma_f32 v76, v76, 0.5, v204
	v_fma_f32 v77, v77, 0.5, v205
	v_fma_f32 v78, v78, 0.5, v206
	v_fma_f32 v79, v79, 0.5, v207
	v_fma_f32 v72, v72, 0.5, v208
	v_fma_f32 v73, v73, 0.5, v209
	v_fma_f32 v74, v74, 0.5, v210
	v_fma_f32 v75, v75, 0.5, v211
	v_add_u32_e32 v242, 0xb0000, v234
	global_load_dwordx4 v[204:207], v242, s[68:69]
	global_load_dwordx4 v[208:211], v242, s[68:69] offset:16
	global_store_dwordx4 v239, v[76:79], s[68:69]
	global_store_dwordx4 v239, v[72:75], s[68:69] offset:16
	v_mul_f32_e32 v237, v76, v76
	v_fmac_f32_e32 v237, v77, v77
	v_fmac_f32_e32 v237, v78, v78
	v_fmac_f32_e32 v237, v79, v79
	v_fmac_f32_e32 v237, v72, v72
	v_fmac_f32_e32 v237, v73, v73
	v_fmac_f32_e32 v237, v74, v74
	v_fmac_f32_e32 v237, v75, v75
	s_waitcnt vmcnt(31)
	v_fma_f32 v68, v68, 0.5, v212
	v_fma_f32 v69, v69, 0.5, v213
	v_fma_f32 v70, v70, 0.5, v214
	v_fma_f32 v71, v71, 0.5, v215
	v_fma_f32 v64, v64, 0.5, v216
	v_fma_f32 v65, v65, 0.5, v217
	v_fma_f32 v66, v66, 0.5, v218
	v_fma_f32 v67, v67, 0.5, v219
	v_add_u32_e32 v242, 0xb0000, v234
	global_load_dwordx4 v[212:215], v242, s[68:69] offset:512
	global_load_dwordx4 v[216:219], v242, s[68:69] offset:528
	global_store_dwordx4 v239, v[68:71], s[68:69] offset:512
	global_store_dwordx4 v239, v[64:67], s[68:69] offset:528
	v_fmac_f32_e32 v237, v68, v68
	v_fmac_f32_e32 v237, v69, v69
	v_fmac_f32_e32 v237, v70, v70
	v_fmac_f32_e32 v237, v71, v71
	v_fmac_f32_e32 v237, v64, v64
	v_fmac_f32_e32 v237, v65, v65
	v_fmac_f32_e32 v237, v66, v66
	v_fmac_f32_e32 v237, v67, v67
	v_mov_b32_e32 v238, v237
	s_nop 1
	v_permlane16_swap_b32_e32 v237, v238
	v_add_f32_e32 v237, v237, v238
	v_mov_b32_e32 v238, v237
	s_nop 1
	v_permlane32_swap_b32_e32 v237, v238
	v_add_f32_e32 v237, v237, v238
	global_store_dword v241, v237, s[66:67]
	v_add_u32_e32 v239, 0x80000, v234
	v_add_u32_e32 v241, 0x2000, v236
	s_waitcnt vmcnt(34)
	v_fma_f32 v60, v60, 0.5, v144
	v_fma_f32 v61, v61, 0.5, v145
	v_fma_f32 v62, v62, 0.5, v146
	v_fma_f32 v63, v63, 0.5, v147
	v_fma_f32 v56, v56, 0.5, v156
	v_fma_f32 v57, v57, 0.5, v157
	v_fma_f32 v58, v58, 0.5, v158
	v_fma_f32 v59, v59, 0.5, v159
	global_store_dwordx4 v239, v[60:63], s[68:69]
	global_store_dwordx4 v239, v[56:59], s[68:69] offset:16
	v_mul_f32_e32 v237, v60, v60
	v_fmac_f32_e32 v237, v61, v61
	v_fmac_f32_e32 v237, v62, v62
	v_fmac_f32_e32 v237, v63, v63
	v_fmac_f32_e32 v237, v56, v56
	v_fmac_f32_e32 v237, v57, v57
	v_fmac_f32_e32 v237, v58, v58
	v_fmac_f32_e32 v237, v59, v59
	s_waitcnt vmcnt(32)
	v_fma_f32 v52, v52, 0.5, v160
	v_fma_f32 v53, v53, 0.5, v161
	v_fma_f32 v54, v54, 0.5, v162
	v_fma_f32 v55, v55, 0.5, v163
	v_fma_f32 v48, v48, 0.5, v164
	v_fma_f32 v49, v49, 0.5, v165
	v_fma_f32 v50, v50, 0.5, v166
	v_fma_f32 v51, v51, 0.5, v167
	global_store_dwordx4 v239, v[52:55], s[68:69] offset:512
	global_store_dwordx4 v239, v[48:51], s[68:69] offset:528
	v_fmac_f32_e32 v237, v52, v52
	v_fmac_f32_e32 v237, v53, v53
	v_fmac_f32_e32 v237, v54, v54
	v_fmac_f32_e32 v237, v55, v55
	v_fmac_f32_e32 v237, v48, v48
	v_fmac_f32_e32 v237, v49, v49
	v_fmac_f32_e32 v237, v50, v50
	v_fmac_f32_e32 v237, v51, v51
	v_mov_b32_e32 v238, v237
	s_nop 1
	v_permlane16_swap_b32_e32 v237, v238
	v_add_f32_e32 v237, v237, v238
	v_mov_b32_e32 v238, v237
	s_nop 1
	v_permlane32_swap_b32_e32 v237, v238
	v_add_f32_e32 v237, v237, v238
	global_store_dword v241, v237, s[66:67]
	v_add_u32_e32 v239, 0x90000, v234
	v_add_u32_e32 v241, 0x2400, v236
	s_waitcnt vmcnt(30)
	v_fma_f32 v44, v44, 0.5, v168
	v_fma_f32 v45, v45, 0.5, v169
	v_fma_f32 v46, v46, 0.5, v170
	v_fma_f32 v47, v47, 0.5, v171
	v_fma_f32 v40, v40, 0.5, v172
	v_fma_f32 v41, v41, 0.5, v173
	v_fma_f32 v42, v42, 0.5, v174
	v_fma_f32 v43, v43, 0.5, v175
	global_store_dwordx4 v239, v[44:47], s[68:69]
	global_store_dwordx4 v239, v[40:43], s[68:69] offset:16
	v_mul_f32_e32 v237, v44, v44
	v_fmac_f32_e32 v237, v45, v45
	v_fmac_f32_e32 v237, v46, v46
	v_fmac_f32_e32 v237, v47, v47
	v_fmac_f32_e32 v237, v40, v40
	v_fmac_f32_e32 v237, v41, v41
	v_fmac_f32_e32 v237, v42, v42
	v_fmac_f32_e32 v237, v43, v43
	s_waitcnt vmcnt(28)
	v_fma_f32 v36, v36, 0.5, v176
	v_fma_f32 v37, v37, 0.5, v177
	v_fma_f32 v38, v38, 0.5, v178
	v_fma_f32 v39, v39, 0.5, v179
	v_fma_f32 v32, v32, 0.5, v180
	v_fma_f32 v33, v33, 0.5, v181
	v_fma_f32 v34, v34, 0.5, v182
	v_fma_f32 v35, v35, 0.5, v183
	global_store_dwordx4 v239, v[36:39], s[68:69] offset:512
	global_store_dwordx4 v239, v[32:35], s[68:69] offset:528
	v_fmac_f32_e32 v237, v36, v36
	v_fmac_f32_e32 v237, v37, v37
	v_fmac_f32_e32 v237, v38, v38
	v_fmac_f32_e32 v237, v39, v39
	v_fmac_f32_e32 v237, v32, v32
	v_fmac_f32_e32 v237, v33, v33
	v_fmac_f32_e32 v237, v34, v34
	v_fmac_f32_e32 v237, v35, v35
	v_mov_b32_e32 v238, v237
	s_nop 1
	v_permlane16_swap_b32_e32 v237, v238
	v_add_f32_e32 v237, v237, v238
	v_mov_b32_e32 v238, v237
	s_nop 1
	v_permlane32_swap_b32_e32 v237, v238
	v_add_f32_e32 v237, v237, v238
	global_store_dword v241, v237, s[66:67]
	v_add_u32_e32 v239, 0xa0000, v234
	v_add_u32_e32 v241, 0x2800, v236
	s_waitcnt vmcnt(26)
	v_fma_f32 v28, v28, 0.5, v184
	v_fma_f32 v29, v29, 0.5, v185
	v_fma_f32 v30, v30, 0.5, v186
	v_fma_f32 v31, v31, 0.5, v187
	v_fma_f32 v24, v24, 0.5, v188
	v_fma_f32 v25, v25, 0.5, v189
	v_fma_f32 v26, v26, 0.5, v190
	v_fma_f32 v27, v27, 0.5, v191
	global_store_dwordx4 v239, v[28:31], s[68:69]
	global_store_dwordx4 v239, v[24:27], s[68:69] offset:16
	v_mul_f32_e32 v237, v28, v28
	v_fmac_f32_e32 v237, v29, v29
	v_fmac_f32_e32 v237, v30, v30
	v_fmac_f32_e32 v237, v31, v31
	v_fmac_f32_e32 v237, v24, v24
	v_fmac_f32_e32 v237, v25, v25
	v_fmac_f32_e32 v237, v26, v26
	v_fmac_f32_e32 v237, v27, v27
	s_waitcnt vmcnt(24)
	v_fma_f32 v20, v20, 0.5, v196
	v_fma_f32 v21, v21, 0.5, v197
	v_fma_f32 v22, v22, 0.5, v198
	v_fma_f32 v23, v23, 0.5, v199
	v_fma_f32 v16, v16, 0.5, v200
	v_fma_f32 v17, v17, 0.5, v201
	v_fma_f32 v18, v18, 0.5, v202
	v_fma_f32 v19, v19, 0.5, v203
	global_store_dwordx4 v239, v[20:23], s[68:69] offset:512
	global_store_dwordx4 v239, v[16:19], s[68:69] offset:528
	v_fmac_f32_e32 v237, v20, v20
	v_fmac_f32_e32 v237, v21, v21
	v_fmac_f32_e32 v237, v22, v22
	v_fmac_f32_e32 v237, v23, v23
	v_fmac_f32_e32 v237, v16, v16
	v_fmac_f32_e32 v237, v17, v17
	v_fmac_f32_e32 v237, v18, v18
	v_fmac_f32_e32 v237, v19, v19
	v_mov_b32_e32 v238, v237
	s_nop 1
	v_permlane16_swap_b32_e32 v237, v238
	v_add_f32_e32 v237, v237, v238
	v_mov_b32_e32 v238, v237
	s_nop 1
	v_permlane32_swap_b32_e32 v237, v238
	v_add_f32_e32 v237, v237, v238
	global_store_dword v241, v237, s[66:67]
	v_add_u32_e32 v239, 0xb0000, v234
	v_add_u32_e32 v241, 0x2c00, v236
	s_waitcnt vmcnt(22)
	v_fma_f32 v12, v12, 0.5, v204
	v_fma_f32 v13, v13, 0.5, v205
	v_fma_f32 v14, v14, 0.5, v206
	v_fma_f32 v15, v15, 0.5, v207
	v_fma_f32 v8, v8, 0.5, v208
	v_fma_f32 v9, v9, 0.5, v209
	v_fma_f32 v10, v10, 0.5, v210
	v_fma_f32 v11, v11, 0.5, v211
	global_store_dwordx4 v239, v[12:15], s[68:69]
	global_store_dwordx4 v239, v[8:11], s[68:69] offset:16
	v_mul_f32_e32 v237, v12, v12
	v_fmac_f32_e32 v237, v13, v13
	v_fmac_f32_e32 v237, v14, v14
	v_fmac_f32_e32 v237, v15, v15
	v_fmac_f32_e32 v237, v8, v8
	v_fmac_f32_e32 v237, v9, v9
	v_fmac_f32_e32 v237, v10, v10
	v_fmac_f32_e32 v237, v11, v11
	s_waitcnt vmcnt(20)
	v_fma_f32 v4, v4, 0.5, v212
	v_fma_f32 v5, v5, 0.5, v213
	v_fma_f32 v6, v6, 0.5, v214
	v_fma_f32 v7, v7, 0.5, v215
	v_fma_f32 v0, v0, 0.5, v216
	v_fma_f32 v1, v1, 0.5, v217
	v_fma_f32 v2, v2, 0.5, v218
	v_fma_f32 v3, v3, 0.5, v219
	global_store_dwordx4 v239, v[4:7], s[68:69] offset:512
	global_store_dwordx4 v239, v[0:3], s[68:69] offset:528
	v_fmac_f32_e32 v237, v4, v4
	v_fmac_f32_e32 v237, v5, v5
	v_fmac_f32_e32 v237, v6, v6
	v_fmac_f32_e32 v237, v7, v7
	v_fmac_f32_e32 v237, v0, v0
	v_fmac_f32_e32 v237, v1, v1
	v_fmac_f32_e32 v237, v2, v2
	v_fmac_f32_e32 v237, v3, v3
	v_mov_b32_e32 v238, v237
	s_nop 1
	v_permlane16_swap_b32_e32 v237, v238
	v_add_f32_e32 v237, v237, v238
	v_mov_b32_e32 v238, v237
	s_nop 1
	v_permlane32_swap_b32_e32 v237, v238
	v_add_f32_e32 v237, v237, v238
	global_store_dword v241, v237, s[66:67]
	s_and_b64 vcc, exec, s[6:7]
	s_mov_b64 s[6:7], -1
	s_cbranch_vccnz .LBB0_3389
	s_andn2_b64 vcc, exec, s[12:13]
	s_cbranch_vccnz .LBB0_3388
	s_barrier
	s_branch .LBB0_3388

	.amdhsa_kernel _Z10fwd_kernel4Args
		.amdhsa_group_segment_fixed_size 0
		.amdhsa_private_segment_fixed_size 0
		.amdhsa_kernarg_size 528
		.amdhsa_user_sgpr_count 2
		.amdhsa_user_sgpr_dispatch_ptr 0
		.amdhsa_user_sgpr_queue_ptr 0
		.amdhsa_user_sgpr_kernarg_segment_ptr 1
		.amdhsa_user_sgpr_dispatch_id 0
		.amdhsa_user_sgpr_kernarg_preload_length 0
		.amdhsa_user_sgpr_kernarg_preload_offset 0
		.amdhsa_user_sgpr_private_segment_size 0
		.amdhsa_uses_dynamic_stack 0
		.amdhsa_enable_private_segment 0
		.amdhsa_system_sgpr_workgroup_id_x 1
		.amdhsa_system_sgpr_workgroup_id_y 0
		.amdhsa_system_sgpr_workgroup_id_z 0
		.amdhsa_system_sgpr_workgroup_info 0
		.amdhsa_system_vgpr_workitem_id 2
		.amdhsa_next_free_vgpr 256
		.amdhsa_next_free_sgpr 100
		.amdhsa_accum_offset 256
		.amdhsa_reserve_vcc 1
		.amdhsa_float_round_mode_32 0
		.amdhsa_float_round_mode_16_64 0
		.amdhsa_float_denorm_mode_32 3
		.amdhsa_float_denorm_mode_16_64 3
		.amdhsa_dx10_clamp 1
		.amdhsa_ieee_mode 1
		.amdhsa_fp16_overflow 0
		.amdhsa_tg_split 0
		.amdhsa_exception_fp_ieee_invalid_op 0
		.amdhsa_exception_fp_denorm_src 0
		.amdhsa_exception_fp_ieee_div_zero 0
		.amdhsa_exception_fp_ieee_overflow 0
		.amdhsa_exception_fp_ieee_underflow 0
		.amdhsa_exception_fp_ieee_inexact 0
		.amdhsa_exception_int_div_zero 0
	.end_amdhsa_kernel

.Lfunc_end0:
	.size	_Z10fwd_kernel4Args, .Lfunc_end0-_Z10fwd_kernel4Args
	.set _Z10fwd_kernel4Args.num_vgpr, 256
	.set _Z10fwd_kernel4Args.num_agpr, 0
	.set _Z10fwd_kernel4Args.numbered_sgpr, 100
	.set _Z10fwd_kernel4Args.num_named_barrier, 0
	.set _Z10fwd_kernel4Args.private_seg_size, 0
	.set _Z10fwd_kernel4Args.uses_vcc, 1
	.set _Z10fwd_kernel4Args.uses_flat_scratch, 0
	.set _Z10fwd_kernel4Args.has_dyn_sized_stack, 0
	.set _Z10fwd_kernel4Args.has_recursion, 0
	.set _Z10fwd_kernel4Args.has_indirect_call, 0

amdhsa.kernels:
  - .agpr_count:     0
    .args:
      - .offset:         0
        .size:           272
        .value_kind:     by_value
      - .offset:         272
        .size:           4
        .value_kind:     hidden_block_count_x
      - .offset:         276
        .size:           4
        .value_kind:     hidden_block_count_y
      - .offset:         280
        .size:           4
        .value_kind:     hidden_block_count_z
      - .offset:         284
        .size:           2
        .value_kind:     hidden_group_size_x
      - .offset:         286
        .size:           2
        .value_kind:     hidden_group_size_y
      - .offset:         288
        .size:           2
        .value_kind:     hidden_group_size_z
      - .offset:         290
        .size:           2
        .value_kind:     hidden_remainder_x
      - .offset:         292
        .size:           2
        .value_kind:     hidden_remainder_y
      - .offset:         294
        .size:           2
        .value_kind:     hidden_remainder_z
      - .offset:         312
        .size:           8
        .value_kind:     hidden_global_offset_x
      - .offset:         320
        .size:           8
        .value_kind:     hidden_global_offset_y
      - .offset:         328
        .size:           8
        .value_kind:     hidden_global_offset_z
      - .offset:         336
        .size:           2
        .value_kind:     hidden_grid_dims
      - .offset:         360
        .size:           8
        .value_kind:     hidden_multigrid_sync_arg
      - .offset:         392
        .size:           4
        .value_kind:     hidden_dynamic_lds_size
    .group_segment_fixed_size: 0
    .kernarg_segment_align: 8
    .kernarg_segment_size: 528
    .language:       OpenCL C
    .language_version:
      - 2
      - 0
    .max_flat_workgroup_size: 512
    .name:           _Z10fwd_kernel4Args
    .private_segment_fixed_size: 0
    .sgpr_count:     106
    .sgpr_spill_count: 0
    .symbol:         _Z10fwd_kernel4Args.kd
    .uniform_work_group_size: 1
    .uses_dynamic_stack: false
    .vgpr_count:     256
    .vgpr_spill_count: 0
    .wavefront_size: 64
